# v37 + GEMM K-loops: MMA-closing barrier issued 2 MFMAs early with the trailing MFMAs at s_setprio 3 (partner's MFMA block starts while they drain)
# speedup vs baseline: 1.0068x; 1.0049x over previous
.LBB0_341:
	v_add_u32_e32 v2, s41, v173
	s_waitcnt lgkmcnt(0)
	ds_read_b128 v[142:145], v2
	ds_read_b128 v[146:149], v2 offset:1024
	ds_read_b128 v[150:153], v2 offset:2048
	ds_read_b128 v[154:157], v2 offset:3072
	v_add_u32_e32 v2, s82, v173
	ds_read_b128 v[158:161], v2
	ds_read_b128 v[162:165], v2 offset:1024
	ds_read_b128 v[166:169], v2 offset:2048
	ds_read_b128 v[180:183], v2 offset:3072
	s_add_i32 s21, s14, 2
	s_add_u32 s16, s12, 0x80
	s_addc_u32 s15, s13, 0
	s_cmp_eq_u32 s18, s14
	s_cselect_b32 s14, s60, s16
	s_cselect_b32 s66, s58, s4
	s_cselect_b32 s15, s61, s15
	s_cselect_b32 s22, s63, s7
	s_cselect_b32 s23, s62, s6
	s_cselect_b32 s17, s65, s20
	s_cselect_b32 s16, s64, s19
	v_lshl_add_u64 v[218:219], s[12:13], 0, v[140:141]
	s_add_i32 m0, s55, 0xc000
	ds_read_b128 v[184:187], v176
	ds_read_b128 v[188:191], v176 offset:1024
	ds_read_b128 v[192:195], v176 offset:2048
	ds_read_b128 v[196:199], v176 offset:3072
	ds_read_b128 v[200:203], v176 offset:4096
	ds_read_b128 v[204:207], v176 offset:5120
	ds_read_b128 v[210:213], v176 offset:6144
	ds_read_b128 v[214:217], v176 offset:7168
	global_load_lds_dwordx4 v[218:219], off
	v_lshl_add_u64 v[218:219], s[12:13], 0, v[4:5]
	s_add_i32 m0, s55, 0xe000
	s_nop 0
	global_load_lds_dwordx4 v[218:219], off
	s_waitcnt vmcnt(8)
	s_waitcnt lgkmcnt(0)
	s_barrier
	s_setprio 1
	s_waitcnt lgkmcnt(0)
	v_mfma_f32_16x16x32_bf16 v[130:133], v[142:145], v[184:187], v[130:133]
	v_mfma_f32_16x16x32_bf16 v[126:129], v[150:153], v[184:187], v[126:129]
	v_mfma_f32_16x16x32_bf16 v[122:125], v[142:145], v[192:195], v[122:125]
	v_mfma_f32_16x16x32_bf16 v[118:121], v[150:153], v[192:195], v[118:121]
	v_mfma_f32_16x16x32_bf16 v[114:117], v[142:145], v[200:203], v[114:117]
	v_mfma_f32_16x16x32_bf16 v[110:113], v[150:153], v[200:203], v[110:113]
	v_mfma_f32_16x16x32_bf16 v[106:109], v[142:145], v[210:213], v[106:109]
	v_mfma_f32_16x16x32_bf16 v[102:105], v[150:153], v[210:213], v[102:105]
	v_mfma_f32_16x16x32_bf16 v[130:133], v[146:149], v[188:191], v[130:133]
	v_mfma_f32_16x16x32_bf16 v[126:129], v[154:157], v[188:191], v[126:129]
	v_mfma_f32_16x16x32_bf16 v[122:125], v[146:149], v[196:199], v[122:125]
	v_mfma_f32_16x16x32_bf16 v[118:121], v[154:157], v[196:199], v[118:121]
	v_mfma_f32_16x16x32_bf16 v[114:117], v[146:149], v[204:207], v[114:117]
	v_mfma_f32_16x16x32_bf16 v[110:113], v[154:157], v[204:207], v[110:113]
	v_mfma_f32_16x16x32_bf16 v[106:109], v[146:149], v[214:217], v[106:109]
	v_mfma_f32_16x16x32_bf16 v[102:105], v[154:157], v[214:217], v[102:105]
	s_setprio 0
	s_setprio 1
	v_mfma_f32_16x16x32_bf16 v[98:101], v[158:161], v[184:187], v[98:101]
	v_mfma_f32_16x16x32_bf16 v[94:97], v[166:169], v[184:187], v[94:97]
	v_mfma_f32_16x16x32_bf16 v[90:93], v[158:161], v[192:195], v[90:93]
	v_mfma_f32_16x16x32_bf16 v[86:89], v[166:169], v[192:195], v[86:89]
	v_mfma_f32_16x16x32_bf16 v[82:85], v[158:161], v[200:203], v[82:85]
	v_mfma_f32_16x16x32_bf16 v[78:81], v[166:169], v[200:203], v[78:81]
	v_mfma_f32_16x16x32_bf16 v[74:77], v[158:161], v[210:213], v[74:77]
	v_mfma_f32_16x16x32_bf16 v[70:73], v[166:169], v[210:213], v[70:73]
	v_mfma_f32_16x16x32_bf16 v[98:101], v[162:165], v[188:191], v[98:101]
	v_mfma_f32_16x16x32_bf16 v[94:97], v[180:183], v[188:191], v[94:97]
	v_mfma_f32_16x16x32_bf16 v[90:93], v[162:165], v[196:199], v[90:93]
	v_mfma_f32_16x16x32_bf16 v[86:89], v[180:183], v[196:199], v[86:89]
	v_mfma_f32_16x16x32_bf16 v[82:85], v[162:165], v[204:207], v[82:85]
	v_mfma_f32_16x16x32_bf16 v[78:81], v[180:183], v[204:207], v[78:81]
	s_setprio 3
	s_barrier
	v_mfma_f32_16x16x32_bf16 v[74:77], v[162:165], v[214:217], v[74:77]
	v_mfma_f32_16x16x32_bf16 v[70:73], v[180:183], v[214:217], v[70:73]
	s_setprio 0
	s_add_i32 s70, s41, s5
	v_mad_u64_u32 v[218:219], s[50:51], s66, v137, v[136:137]
	s_mov_b32 m0, s70
	v_mad_u64_u32 v[222:223], s[50:51], s66, v170, v[136:137]
	ds_read_b128 v[184:187], v176 offset:16384
	ds_read_b128 v[188:191], v176 offset:17408
	ds_read_b128 v[192:195], v176 offset:18432
	ds_read_b128 v[196:199], v176 offset:19456
	ds_read_b128 v[200:203], v176 offset:20480
	ds_read_b128 v[204:207], v176 offset:21504
	ds_read_b128 v[210:213], v176 offset:22528
	ds_read_b128 v[214:217], v176 offset:23552
	v_mov_b32_e32 v219, v3
	global_load_lds_dwordx4 v218, s[16:17]
	v_mov_b32_e32 v223, v3
	s_add_i32 m0, s70, 0x2000
	v_lshl_add_u64 v[220:221], s[16:17], 0, v[218:219]
	v_lshl_add_u64 v[224:225], s[16:17], 0, v[222:223]
	global_load_lds_dwordx4 v222, s[16:17]
	s_add_u32 s16, s16, s23
	s_addc_u32 s17, s17, s22
	s_add_i32 s50, s82, s5
	s_mov_b32 m0, s50
	v_lshl_add_u64 v[226:227], s[16:17], 0, v[218:219]
	global_load_lds_dwordx4 v218, s[16:17]
	s_add_i32 m0, s50, 0x2000
	v_lshl_add_u64 v[218:219], s[16:17], 0, v[222:223]
	global_load_lds_dwordx4 v222, s[16:17]
	v_mad_u64_u32 v[222:223], s[16:17], s66, v135, v[136:137]
	s_mov_b32 m0, s55
	v_mad_u64_u32 v[230:231], s[16:17], s66, v139, v[136:137]
	global_load_lds_dwordx4 v222, s[14:15]
	s_mov_b32 m0, s56
	v_mov_b32_e32 v223, v3
	global_load_lds_dwordx4 v230, s[14:15]
	s_waitcnt vmcnt(8)
	s_waitcnt lgkmcnt(0)
	v_mov_b32_e32 v231, v3
	v_lshl_add_u64 v[228:229], s[14:15], 0, v[222:223]
	v_lshl_add_u64 v[232:233], s[14:15], 0, v[230:231]
	s_barrier
	s_setprio 1
	s_waitcnt lgkmcnt(0)
	v_mfma_f32_16x16x32_bf16 v[66:69], v[142:145], v[184:187], v[66:69]
	v_mfma_f32_16x16x32_bf16 v[62:65], v[150:153], v[184:187], v[62:65]
	v_mfma_f32_16x16x32_bf16 v[58:61], v[142:145], v[192:195], v[58:61]
	v_mfma_f32_16x16x32_bf16 v[54:57], v[150:153], v[192:195], v[54:57]
	v_mfma_f32_16x16x32_bf16 v[50:53], v[142:145], v[200:203], v[50:53]
	v_mfma_f32_16x16x32_bf16 v[46:49], v[150:153], v[200:203], v[46:49]
	v_mfma_f32_16x16x32_bf16 v[42:45], v[142:145], v[210:213], v[42:45]
	v_mfma_f32_16x16x32_bf16 v[38:41], v[150:153], v[210:213], v[38:41]
	v_mfma_f32_16x16x32_bf16 v[66:69], v[146:149], v[188:191], v[66:69]
	v_mfma_f32_16x16x32_bf16 v[62:65], v[154:157], v[188:191], v[62:65]
	v_mfma_f32_16x16x32_bf16 v[58:61], v[146:149], v[196:199], v[58:61]
	v_mfma_f32_16x16x32_bf16 v[54:57], v[154:157], v[196:199], v[54:57]
	v_mfma_f32_16x16x32_bf16 v[50:53], v[146:149], v[204:207], v[50:53]
	v_mfma_f32_16x16x32_bf16 v[46:49], v[154:157], v[204:207], v[46:49]
	v_mfma_f32_16x16x32_bf16 v[42:45], v[146:149], v[214:217], v[42:45]
	v_mfma_f32_16x16x32_bf16 v[38:41], v[154:157], v[214:217], v[38:41]
	s_setprio 0
	s_setprio 1
	v_mfma_f32_16x16x32_bf16 v[34:37], v[158:161], v[184:187], v[34:37]
	v_mfma_f32_16x16x32_bf16 v[30:33], v[166:169], v[184:187], v[30:33]
	v_mfma_f32_16x16x32_bf16 v[26:29], v[158:161], v[192:195], v[26:29]
	v_mfma_f32_16x16x32_bf16 v[22:25], v[166:169], v[192:195], v[22:25]
	v_mfma_f32_16x16x32_bf16 v[18:21], v[158:161], v[200:203], v[18:21]
	v_mfma_f32_16x16x32_bf16 v[14:17], v[166:169], v[200:203], v[14:17]
	v_mfma_f32_16x16x32_bf16 v[10:13], v[158:161], v[210:213], v[10:13]
	v_mfma_f32_16x16x32_bf16 v[6:9], v[166:169], v[210:213], v[6:9]
	v_mfma_f32_16x16x32_bf16 v[34:37], v[162:165], v[188:191], v[34:37]
	v_mfma_f32_16x16x32_bf16 v[30:33], v[180:183], v[188:191], v[30:33]
	v_mfma_f32_16x16x32_bf16 v[26:29], v[162:165], v[196:199], v[26:29]
	v_mfma_f32_16x16x32_bf16 v[22:25], v[180:183], v[196:199], v[22:25]
	v_mfma_f32_16x16x32_bf16 v[18:21], v[162:165], v[204:207], v[18:21]
	v_mfma_f32_16x16x32_bf16 v[14:17], v[180:183], v[204:207], v[14:17]
	s_setprio 3
	s_barrier
	v_mfma_f32_16x16x32_bf16 v[10:13], v[162:165], v[214:217], v[10:13]
	v_mfma_f32_16x16x32_bf16 v[6:9], v[180:183], v[214:217], v[6:9]
	s_setprio 0
	s_add_i32 s16, 0, 0x18000
	v_add_u32_e32 v2, s16, v173
	s_add_i32 s17, 0, 0x1c000
	ds_read_b128 v[142:145], v2
	ds_read_b128 v[146:149], v2 offset:1024
	ds_read_b128 v[150:153], v2 offset:2048
	ds_read_b128 v[154:157], v2 offset:3072
	v_add_u32_e32 v2, s17, v173
	ds_read_b128 v[158:161], v2
	ds_read_b128 v[162:165], v2 offset:1024
	ds_read_b128 v[166:169], v2 offset:2048
	ds_read_b128 v[180:183], v2 offset:3072
	s_add_u32 s14, s14, s23
	s_addc_u32 s15, s15, s22
	s_mov_b32 m0, s57
	ds_read_b128 v[184:187], v176 offset:32768
	ds_read_b128 v[188:191], v176 offset:33792
	ds_read_b128 v[192:195], v176 offset:34816
	ds_read_b128 v[196:199], v176 offset:35840
	ds_read_b128 v[200:203], v176 offset:36864
	ds_read_b128 v[204:207], v176 offset:37888
	ds_read_b128 v[210:213], v176 offset:38912
	ds_read_b128 v[214:217], v176 offset:39936
	global_load_lds_dwordx4 v222, s[14:15]
	s_mov_b32 m0, s0
	s_nop 0
	global_load_lds_dwordx4 v230, s[14:15]
	s_waitcnt vmcnt(8)
	s_waitcnt lgkmcnt(0)
	s_barrier
	s_setprio 1
	s_waitcnt lgkmcnt(0)
	v_mfma_f32_16x16x32_bf16 v[130:133], v[142:145], v[184:187], v[130:133]
	v_mfma_f32_16x16x32_bf16 v[126:129], v[150:153], v[184:187], v[126:129]
	v_mfma_f32_16x16x32_bf16 v[122:125], v[142:145], v[192:195], v[122:125]
	v_mfma_f32_16x16x32_bf16 v[118:121], v[150:153], v[192:195], v[118:121]
	v_mfma_f32_16x16x32_bf16 v[114:117], v[142:145], v[200:203], v[114:117]
	v_mfma_f32_16x16x32_bf16 v[110:113], v[150:153], v[200:203], v[110:113]
	v_mfma_f32_16x16x32_bf16 v[106:109], v[142:145], v[210:213], v[106:109]
	v_mfma_f32_16x16x32_bf16 v[102:105], v[150:153], v[210:213], v[102:105]
	v_mfma_f32_16x16x32_bf16 v[130:133], v[146:149], v[188:191], v[130:133]
	v_mfma_f32_16x16x32_bf16 v[126:129], v[154:157], v[188:191], v[126:129]
	v_mfma_f32_16x16x32_bf16 v[122:125], v[146:149], v[196:199], v[122:125]
	v_mfma_f32_16x16x32_bf16 v[118:121], v[154:157], v[196:199], v[118:121]
	v_mfma_f32_16x16x32_bf16 v[114:117], v[146:149], v[204:207], v[114:117]
	v_mfma_f32_16x16x32_bf16 v[110:113], v[154:157], v[204:207], v[110:113]
	v_mfma_f32_16x16x32_bf16 v[106:109], v[146:149], v[214:217], v[106:109]
	v_mfma_f32_16x16x32_bf16 v[102:105], v[154:157], v[214:217], v[102:105]
	s_setprio 0
	s_setprio 1
	v_mfma_f32_16x16x32_bf16 v[98:101], v[158:161], v[184:187], v[98:101]
	v_mfma_f32_16x16x32_bf16 v[94:97], v[166:169], v[184:187], v[94:97]
	v_mfma_f32_16x16x32_bf16 v[90:93], v[158:161], v[192:195], v[90:93]
	v_mfma_f32_16x16x32_bf16 v[86:89], v[166:169], v[192:195], v[86:89]
	v_mfma_f32_16x16x32_bf16 v[82:85], v[158:161], v[200:203], v[82:85]
	v_mfma_f32_16x16x32_bf16 v[78:81], v[166:169], v[200:203], v[78:81]
	v_mfma_f32_16x16x32_bf16 v[74:77], v[158:161], v[210:213], v[74:77]
	v_mfma_f32_16x16x32_bf16 v[70:73], v[166:169], v[210:213], v[70:73]
	v_mfma_f32_16x16x32_bf16 v[98:101], v[162:165], v[188:191], v[98:101]
	v_mfma_f32_16x16x32_bf16 v[94:97], v[180:183], v[188:191], v[94:97]
	v_mfma_f32_16x16x32_bf16 v[90:93], v[162:165], v[196:199], v[90:93]
	v_mfma_f32_16x16x32_bf16 v[86:89], v[180:183], v[196:199], v[86:89]
	v_mfma_f32_16x16x32_bf16 v[82:85], v[162:165], v[204:207], v[82:85]
	v_mfma_f32_16x16x32_bf16 v[78:81], v[180:183], v[204:207], v[78:81]
	s_setprio 3
	s_barrier
	v_mfma_f32_16x16x32_bf16 v[74:77], v[162:165], v[214:217], v[74:77]
	v_mfma_f32_16x16x32_bf16 v[70:73], v[180:183], v[214:217], v[70:73]
	s_setprio 0
	s_add_i32 s14, s16, s5
	v_lshl_add_u64 v[220:221], v[220:221], 0, s[90:91]
	s_mov_b32 m0, s14
	ds_read_b128 v[184:187], v176 offset:49152
	ds_read_b128 v[188:191], v176 offset:50176
	ds_read_b128 v[192:195], v176 offset:51200
	ds_read_b128 v[196:199], v176 offset:52224
	ds_read_b128 v[200:203], v176 offset:53248
	ds_read_b128 v[204:207], v176 offset:54272
	ds_read_b128 v[210:213], v176 offset:55296
	ds_read_b128 v[214:217], v176 offset:56320
	global_load_lds_dwordx4 v[220:221], off
	v_lshl_add_u64 v[220:221], v[224:225], 0, s[90:91]
	s_add_i32 m0, s14, 0x2000
	s_add_i32 s14, s17, s5
	global_load_lds_dwordx4 v[220:221], off
	v_lshl_add_u64 v[220:221], v[226:227], 0, s[90:91]
	s_mov_b32 m0, s14
	v_lshl_add_u64 v[218:219], v[218:219], 0, s[90:91]
	global_load_lds_dwordx4 v[220:221], off
	s_add_i32 m0, s14, 0x2000
	s_nop 0
	global_load_lds_dwordx4 v[218:219], off
	v_lshl_add_u64 v[218:219], v[228:229], 0, s[90:91]
	s_mov_b32 m0, s43
	s_nop 0
	global_load_lds_dwordx4 v[218:219], off
	v_lshl_add_u64 v[218:219], v[232:233], 0, s[90:91]
	s_mov_b32 m0, s76
	s_nop 0
	global_load_lds_dwordx4 v[218:219], off
	s_waitcnt vmcnt(8)
	s_waitcnt lgkmcnt(0)
	s_barrier
	s_setprio 1
	s_waitcnt lgkmcnt(0)
	v_mfma_f32_16x16x32_bf16 v[66:69], v[142:145], v[184:187], v[66:69]
	v_mfma_f32_16x16x32_bf16 v[62:65], v[150:153], v[184:187], v[62:65]
	v_mfma_f32_16x16x32_bf16 v[58:61], v[142:145], v[192:195], v[58:61]
	v_mfma_f32_16x16x32_bf16 v[54:57], v[150:153], v[192:195], v[54:57]
	v_mfma_f32_16x16x32_bf16 v[50:53], v[142:145], v[200:203], v[50:53]
	v_mfma_f32_16x16x32_bf16 v[46:49], v[150:153], v[200:203], v[46:49]
	v_mfma_f32_16x16x32_bf16 v[42:45], v[142:145], v[210:213], v[42:45]
	v_mfma_f32_16x16x32_bf16 v[38:41], v[150:153], v[210:213], v[38:41]
	v_mfma_f32_16x16x32_bf16 v[66:69], v[146:149], v[188:191], v[66:69]
	v_mfma_f32_16x16x32_bf16 v[62:65], v[154:157], v[188:191], v[62:65]
	v_mfma_f32_16x16x32_bf16 v[58:61], v[146:149], v[196:199], v[58:61]
	v_mfma_f32_16x16x32_bf16 v[54:57], v[154:157], v[196:199], v[54:57]
	v_mfma_f32_16x16x32_bf16 v[50:53], v[146:149], v[204:207], v[50:53]
	v_mfma_f32_16x16x32_bf16 v[46:49], v[154:157], v[204:207], v[46:49]
	v_mfma_f32_16x16x32_bf16 v[42:45], v[146:149], v[214:217], v[42:45]
	v_mfma_f32_16x16x32_bf16 v[38:41], v[154:157], v[214:217], v[38:41]
	s_setprio 0
	s_setprio 1
	v_mfma_f32_16x16x32_bf16 v[34:37], v[158:161], v[184:187], v[34:37]
	v_mfma_f32_16x16x32_bf16 v[30:33], v[166:169], v[184:187], v[30:33]
	v_mfma_f32_16x16x32_bf16 v[26:29], v[158:161], v[192:195], v[26:29]
	v_mfma_f32_16x16x32_bf16 v[22:25], v[166:169], v[192:195], v[22:25]
	v_mfma_f32_16x16x32_bf16 v[18:21], v[158:161], v[200:203], v[18:21]
	v_mfma_f32_16x16x32_bf16 v[14:17], v[166:169], v[200:203], v[14:17]
	v_mfma_f32_16x16x32_bf16 v[10:13], v[158:161], v[210:213], v[10:13]
	v_mfma_f32_16x16x32_bf16 v[6:9], v[166:169], v[210:213], v[6:9]
	v_mfma_f32_16x16x32_bf16 v[34:37], v[162:165], v[188:191], v[34:37]
	v_mfma_f32_16x16x32_bf16 v[30:33], v[180:183], v[188:191], v[30:33]
	v_mfma_f32_16x16x32_bf16 v[26:29], v[162:165], v[196:199], v[26:29]
	v_mfma_f32_16x16x32_bf16 v[22:25], v[180:183], v[196:199], v[22:25]
	v_mfma_f32_16x16x32_bf16 v[18:21], v[162:165], v[204:207], v[18:21]
	v_mfma_f32_16x16x32_bf16 v[14:17], v[180:183], v[204:207], v[14:17]
	s_setprio 3
	s_barrier
	v_mfma_f32_16x16x32_bf16 v[10:13], v[162:165], v[214:217], v[10:13]
	v_mfma_f32_16x16x32_bf16 v[6:9], v[180:183], v[214:217], v[6:9]
	s_setprio 0
	s_add_u32 s19, s19, 0x100
	s_addc_u32 s20, s20, 0
	s_add_u32 s12, s12, 0x100
	s_addc_u32 s13, s13, 0
	s_cmp_ge_i32 s21, s27
	s_mov_b32 s14, s21
	s_cbranch_scc0 .LBB0_341

.LBB0_626:
	ds_read_b128 v[130:133], v170
	ds_read_b128 v[150:153], v170 offset:1024
	ds_read_b128 v[154:157], v170 offset:2048
	ds_read_b128 v[158:161], v170 offset:3072
	ds_read_b128 v[162:165], v171
	ds_read_b128 v[174:177], v171 offset:1024
	ds_read_b128 v[178:181], v171 offset:2048
	ds_read_b128 v[182:185], v171 offset:3072
	s_add_i32 s46, s44, 2
	s_add_u32 s47, s0, 0x80
	s_addc_u32 s45, s1, 0
	s_cmp_eq_u32 s80, s44
	s_cselect_b32 s44, s40, s47
	s_cselect_b32 s45, s41, s45
	s_cselect_b32 vcc_hi, s43, s96
	s_cselect_b32 vcc_lo, s42, s95
	v_lshl_add_u64 v[166:167], s[0:1], 0, v[146:147]
	s_add_i32 m0, s56, 0xc000
	ds_read_b128 v[186:189], v172
	ds_read_b128 v[190:193], v172 offset:1024
	ds_read_b128 v[194:197], v172 offset:2048
	ds_read_b128 v[198:201], v172 offset:3072
	ds_read_b128 v[202:205], v172 offset:4096
	ds_read_b128 v[210:213], v172 offset:5120
	ds_read_b128 v[214:217], v172 offset:6144
	ds_read_b128 v[218:221], v172 offset:7168
	global_load_lds_dwordx4 v[166:167], off
	v_lshl_add_u64 v[166:167], s[0:1], 0, v[144:145]
	s_add_i32 m0, s56, 0xe000
	s_nop 0
	global_load_lds_dwordx4 v[166:167], off
	s_waitcnt vmcnt(8)
	s_waitcnt lgkmcnt(0)
	s_barrier
	s_setprio 1
	s_waitcnt lgkmcnt(0)
	v_mfma_f32_16x16x32_bf16 v[122:125], v[130:133], v[186:189], v[122:125]
	v_mfma_f32_16x16x32_bf16 v[126:129], v[154:157], v[186:189], v[126:129]
	v_mfma_f32_16x16x32_bf16 v[110:113], v[130:133], v[194:197], v[110:113]
	v_mfma_f32_16x16x32_bf16 v[106:109], v[154:157], v[194:197], v[106:109]
	v_mfma_f32_16x16x32_bf16 v[94:97], v[130:133], v[202:205], v[94:97]
	v_mfma_f32_16x16x32_bf16 v[90:93], v[154:157], v[202:205], v[90:93]
	v_mfma_f32_16x16x32_bf16 v[78:81], v[130:133], v[214:217], v[78:81]
	v_mfma_f32_16x16x32_bf16 v[74:77], v[154:157], v[214:217], v[74:77]
	v_mfma_f32_16x16x32_bf16 v[122:125], v[150:153], v[190:193], v[122:125]
	v_mfma_f32_16x16x32_bf16 v[126:129], v[158:161], v[190:193], v[126:129]
	v_mfma_f32_16x16x32_bf16 v[110:113], v[150:153], v[198:201], v[110:113]
	v_mfma_f32_16x16x32_bf16 v[106:109], v[158:161], v[198:201], v[106:109]
	v_mfma_f32_16x16x32_bf16 v[94:97], v[150:153], v[210:213], v[94:97]
	v_mfma_f32_16x16x32_bf16 v[90:93], v[158:161], v[210:213], v[90:93]
	v_mfma_f32_16x16x32_bf16 v[78:81], v[150:153], v[218:221], v[78:81]
	v_mfma_f32_16x16x32_bf16 v[74:77], v[158:161], v[218:221], v[74:77]
	s_setprio 0
	s_setprio 1
	v_mfma_f32_16x16x32_bf16 v[118:121], v[162:165], v[186:189], v[118:121]
	v_mfma_f32_16x16x32_bf16 v[114:117], v[178:181], v[186:189], v[114:117]
	v_mfma_f32_16x16x32_bf16 v[102:105], v[162:165], v[194:197], v[102:105]
	v_mfma_f32_16x16x32_bf16 v[98:101], v[178:181], v[194:197], v[98:101]
	v_mfma_f32_16x16x32_bf16 v[86:89], v[162:165], v[202:205], v[86:89]
	v_mfma_f32_16x16x32_bf16 v[82:85], v[178:181], v[202:205], v[82:85]
	v_mfma_f32_16x16x32_bf16 v[70:73], v[162:165], v[214:217], v[70:73]
	v_mfma_f32_16x16x32_bf16 v[66:69], v[178:181], v[214:217], v[66:69]
	v_mfma_f32_16x16x32_bf16 v[118:121], v[174:177], v[190:193], v[118:121]
	v_mfma_f32_16x16x32_bf16 v[114:117], v[182:185], v[190:193], v[114:117]
	v_mfma_f32_16x16x32_bf16 v[102:105], v[174:177], v[198:201], v[102:105]
	v_mfma_f32_16x16x32_bf16 v[98:101], v[182:185], v[198:201], v[98:101]
	v_mfma_f32_16x16x32_bf16 v[86:89], v[174:177], v[210:213], v[86:89]
	v_mfma_f32_16x16x32_bf16 v[82:85], v[182:185], v[210:213], v[82:85]
	s_setprio 3
	s_barrier
	v_mfma_f32_16x16x32_bf16 v[70:73], v[174:177], v[218:221], v[70:73]
	v_mfma_f32_16x16x32_bf16 v[66:69], v[182:185], v[218:221], v[66:69]
	s_setprio 0
	s_add_i32 s47, s86, s55
	v_lshl_add_u64 v[166:167], vcc, 0, v[136:137]
	s_mov_b32 m0, s47
	ds_read_b128 v[186:189], v172 offset:16384
	ds_read_b128 v[190:193], v172 offset:17408
	ds_read_b128 v[194:197], v172 offset:18432
	ds_read_b128 v[198:201], v172 offset:19456
	ds_read_b128 v[202:205], v172 offset:20480
	ds_read_b128 v[210:213], v172 offset:21504
	ds_read_b128 v[214:217], v172 offset:22528
	ds_read_b128 v[218:221], v172 offset:23552
	global_load_lds_dwordx4 v[166:167], off
	s_add_i32 m0, s47, 0x2000
	v_lshl_add_u64 v[206:207], vcc, 0, v[138:139]
	s_add_u32 vcc_lo, vcc_lo, s16
	s_addc_u32 vcc_hi, vcc_hi, s17
	s_add_i32 s47, s87, s55
	global_load_lds_dwordx4 v[206:207], off
	v_lshl_add_u64 v[222:223], vcc, 0, v[136:137]
	s_mov_b32 m0, s47
	v_lshl_add_u64 v[224:225], vcc, 0, v[138:139]
	global_load_lds_dwordx4 v[222:223], off
	s_add_i32 m0, s47, 0x2000
	v_lshl_add_u64 v[226:227], s[44:45], 0, v[140:141]
	global_load_lds_dwordx4 v[224:225], off
	s_mov_b32 m0, s56
	v_lshl_add_u64 v[228:229], s[44:45], 0, v[142:143]
	global_load_lds_dwordx4 v[226:227], off
	s_mov_b32 m0, s57
	s_nop 0
	global_load_lds_dwordx4 v[228:229], off
	s_waitcnt vmcnt(8)
	s_waitcnt lgkmcnt(0)
	s_barrier
	s_setprio 1
	s_waitcnt lgkmcnt(0)
	v_mfma_f32_16x16x32_bf16 v[62:65], v[130:133], v[186:189], v[62:65]
	v_mfma_f32_16x16x32_bf16 v[58:61], v[154:157], v[186:189], v[58:61]
	v_mfma_f32_16x16x32_bf16 v[46:49], v[130:133], v[194:197], v[46:49]
	v_mfma_f32_16x16x32_bf16 v[42:45], v[154:157], v[194:197], v[42:45]
	v_mfma_f32_16x16x32_bf16 v[30:33], v[130:133], v[202:205], v[30:33]
	v_mfma_f32_16x16x32_bf16 v[26:29], v[154:157], v[202:205], v[26:29]
	v_mfma_f32_16x16x32_bf16 v[14:17], v[130:133], v[214:217], v[14:17]
	v_mfma_f32_16x16x32_bf16 v[10:13], v[154:157], v[214:217], v[10:13]
	v_mfma_f32_16x16x32_bf16 v[62:65], v[150:153], v[190:193], v[62:65]
	v_mfma_f32_16x16x32_bf16 v[58:61], v[158:161], v[190:193], v[58:61]
	v_mfma_f32_16x16x32_bf16 v[46:49], v[150:153], v[198:201], v[46:49]
	v_mfma_f32_16x16x32_bf16 v[42:45], v[158:161], v[198:201], v[42:45]
	v_mfma_f32_16x16x32_bf16 v[30:33], v[150:153], v[210:213], v[30:33]
	v_mfma_f32_16x16x32_bf16 v[26:29], v[158:161], v[210:213], v[26:29]
	v_mfma_f32_16x16x32_bf16 v[14:17], v[150:153], v[218:221], v[14:17]
	v_mfma_f32_16x16x32_bf16 v[10:13], v[158:161], v[218:221], v[10:13]
	s_setprio 0
	s_setprio 1
	v_mfma_f32_16x16x32_bf16 v[54:57], v[162:165], v[186:189], v[54:57]
	v_mfma_f32_16x16x32_bf16 v[50:53], v[178:181], v[186:189], v[50:53]
	v_mfma_f32_16x16x32_bf16 v[38:41], v[162:165], v[194:197], v[38:41]
	v_mfma_f32_16x16x32_bf16 v[34:37], v[178:181], v[194:197], v[34:37]
	v_mfma_f32_16x16x32_bf16 v[22:25], v[162:165], v[202:205], v[22:25]
	v_mfma_f32_16x16x32_bf16 v[18:21], v[178:181], v[202:205], v[18:21]
	v_mfma_f32_16x16x32_bf16 v[6:9], v[162:165], v[214:217], v[6:9]
	v_mfma_f32_16x16x32_bf16 v[2:5], v[178:181], v[214:217], v[2:5]
	v_mfma_f32_16x16x32_bf16 v[54:57], v[174:177], v[190:193], v[54:57]
	v_mfma_f32_16x16x32_bf16 v[50:53], v[182:185], v[190:193], v[50:53]
	v_mfma_f32_16x16x32_bf16 v[38:41], v[174:177], v[198:201], v[38:41]
	v_mfma_f32_16x16x32_bf16 v[34:37], v[182:185], v[198:201], v[34:37]
	v_mfma_f32_16x16x32_bf16 v[22:25], v[174:177], v[210:213], v[22:25]
	v_mfma_f32_16x16x32_bf16 v[18:21], v[182:185], v[210:213], v[18:21]
	s_setprio 3
	s_barrier
	v_mfma_f32_16x16x32_bf16 v[6:9], v[174:177], v[218:221], v[6:9]
	v_mfma_f32_16x16x32_bf16 v[2:5], v[182:185], v[218:221], v[2:5]
	s_setprio 0
	s_add_i32 s47, 0, 0x18000
	s_add_i32 vcc_lo, 0, 0x1c000
	v_add_u32_e32 v158, s47, v169
	v_add_u32_e32 v182, vcc_lo, v169
	ds_read_b128 v[130:133], v158
	ds_read_b128 v[150:153], v158 offset:1024
	ds_read_b128 v[154:157], v158 offset:2048
	ds_read_b128 v[158:161], v158 offset:3072
	ds_read_b128 v[162:165], v182
	ds_read_b128 v[174:177], v182 offset:1024
	ds_read_b128 v[178:181], v182 offset:2048
	ds_read_b128 v[182:185], v182 offset:3072
	s_add_u32 s44, s44, s16
	s_addc_u32 s45, s45, s17
	s_mov_b32 m0, s58
	v_lshl_add_u64 v[230:231], s[44:45], 0, v[140:141]
	ds_read_b128 v[186:189], v172 offset:32768
	ds_read_b128 v[190:193], v172 offset:33792
	ds_read_b128 v[194:197], v172 offset:34816
	ds_read_b128 v[198:201], v172 offset:35840
	ds_read_b128 v[202:205], v172 offset:36864
	ds_read_b128 v[210:213], v172 offset:37888
	ds_read_b128 v[214:217], v172 offset:38912
	ds_read_b128 v[218:221], v172 offset:39936
	global_load_lds_dwordx4 v[230:231], off
	v_lshl_add_u64 v[230:231], s[44:45], 0, v[142:143]
	s_mov_b32 m0, s59
	s_nop 0
	global_load_lds_dwordx4 v[230:231], off
	s_waitcnt vmcnt(8)
	s_waitcnt lgkmcnt(0)
	s_barrier
	s_setprio 1
	s_waitcnt lgkmcnt(0)
	v_mfma_f32_16x16x32_bf16 v[122:125], v[130:133], v[186:189], v[122:125]
	v_mfma_f32_16x16x32_bf16 v[126:129], v[154:157], v[186:189], v[126:129]
	v_mfma_f32_16x16x32_bf16 v[110:113], v[130:133], v[194:197], v[110:113]
	v_mfma_f32_16x16x32_bf16 v[106:109], v[154:157], v[194:197], v[106:109]
	v_mfma_f32_16x16x32_bf16 v[94:97], v[130:133], v[202:205], v[94:97]
	v_mfma_f32_16x16x32_bf16 v[90:93], v[154:157], v[202:205], v[90:93]
	v_mfma_f32_16x16x32_bf16 v[78:81], v[130:133], v[214:217], v[78:81]
	v_mfma_f32_16x16x32_bf16 v[74:77], v[154:157], v[214:217], v[74:77]
	v_mfma_f32_16x16x32_bf16 v[122:125], v[150:153], v[190:193], v[122:125]
	v_mfma_f32_16x16x32_bf16 v[126:129], v[158:161], v[190:193], v[126:129]
	v_mfma_f32_16x16x32_bf16 v[110:113], v[150:153], v[198:201], v[110:113]
	v_mfma_f32_16x16x32_bf16 v[106:109], v[158:161], v[198:201], v[106:109]
	v_mfma_f32_16x16x32_bf16 v[94:97], v[150:153], v[210:213], v[94:97]
	v_mfma_f32_16x16x32_bf16 v[90:93], v[158:161], v[210:213], v[90:93]
	v_mfma_f32_16x16x32_bf16 v[78:81], v[150:153], v[218:221], v[78:81]
	v_mfma_f32_16x16x32_bf16 v[74:77], v[158:161], v[218:221], v[74:77]
	s_setprio 0
	s_setprio 1
	v_mfma_f32_16x16x32_bf16 v[118:121], v[162:165], v[186:189], v[118:121]
	v_mfma_f32_16x16x32_bf16 v[114:117], v[178:181], v[186:189], v[114:117]
	v_mfma_f32_16x16x32_bf16 v[102:105], v[162:165], v[194:197], v[102:105]
	v_mfma_f32_16x16x32_bf16 v[98:101], v[178:181], v[194:197], v[98:101]
	v_mfma_f32_16x16x32_bf16 v[86:89], v[162:165], v[202:205], v[86:89]
	v_mfma_f32_16x16x32_bf16 v[82:85], v[178:181], v[202:205], v[82:85]
	v_mfma_f32_16x16x32_bf16 v[70:73], v[162:165], v[214:217], v[70:73]
	v_mfma_f32_16x16x32_bf16 v[66:69], v[178:181], v[214:217], v[66:69]
	v_mfma_f32_16x16x32_bf16 v[118:121], v[174:177], v[190:193], v[118:121]
	v_mfma_f32_16x16x32_bf16 v[114:117], v[182:185], v[190:193], v[114:117]
	v_mfma_f32_16x16x32_bf16 v[102:105], v[174:177], v[198:201], v[102:105]
	v_mfma_f32_16x16x32_bf16 v[98:101], v[182:185], v[198:201], v[98:101]
	v_mfma_f32_16x16x32_bf16 v[86:89], v[174:177], v[210:213], v[86:89]
	v_mfma_f32_16x16x32_bf16 v[82:85], v[182:185], v[210:213], v[82:85]
	s_setprio 3
	s_barrier
	v_mfma_f32_16x16x32_bf16 v[70:73], v[174:177], v[218:221], v[70:73]
	v_mfma_f32_16x16x32_bf16 v[66:69], v[182:185], v[218:221], v[66:69]
	s_setprio 0
	s_add_i32 s44, s47, s55
	v_lshl_add_u64 v[166:167], v[166:167], 0, s[24:25]
	s_mov_b32 m0, s44
	ds_read_b128 v[186:189], v172 offset:49152
	ds_read_b128 v[190:193], v172 offset:50176
	ds_read_b128 v[194:197], v172 offset:51200
	ds_read_b128 v[198:201], v172 offset:52224
	ds_read_b128 v[202:205], v172 offset:53248
	ds_read_b128 v[210:213], v172 offset:54272
	ds_read_b128 v[214:217], v172 offset:55296
	ds_read_b128 v[218:221], v172 offset:56320
	global_load_lds_dwordx4 v[166:167], off
	v_lshl_add_u64 v[166:167], v[206:207], 0, s[24:25]
	s_add_i32 m0, s44, 0x2000
	s_add_i32 s44, vcc_lo, s55
	global_load_lds_dwordx4 v[166:167], off
	v_lshl_add_u64 v[166:167], v[222:223], 0, s[24:25]
	s_mov_b32 m0, s44
	s_nop 0
	global_load_lds_dwordx4 v[166:167], off
	v_lshl_add_u64 v[166:167], v[224:225], 0, s[24:25]
	s_add_i32 m0, s44, 0x2000
	s_nop 0
	global_load_lds_dwordx4 v[166:167], off
	v_lshl_add_u64 v[166:167], v[226:227], 0, s[24:25]
	s_mov_b32 m0, s63
	s_nop 0
	global_load_lds_dwordx4 v[166:167], off
	v_lshl_add_u64 v[166:167], v[228:229], 0, s[24:25]
	s_mov_b32 m0, s64
	s_nop 0
	global_load_lds_dwordx4 v[166:167], off
	s_waitcnt vmcnt(8)
	s_waitcnt lgkmcnt(0)
	s_barrier
	s_setprio 1
	s_waitcnt lgkmcnt(0)
	v_mfma_f32_16x16x32_bf16 v[62:65], v[130:133], v[186:189], v[62:65]
	v_mfma_f32_16x16x32_bf16 v[58:61], v[154:157], v[186:189], v[58:61]
	v_mfma_f32_16x16x32_bf16 v[46:49], v[130:133], v[194:197], v[46:49]
	v_mfma_f32_16x16x32_bf16 v[42:45], v[154:157], v[194:197], v[42:45]
	v_mfma_f32_16x16x32_bf16 v[30:33], v[130:133], v[202:205], v[30:33]
	v_mfma_f32_16x16x32_bf16 v[26:29], v[154:157], v[202:205], v[26:29]
	v_mfma_f32_16x16x32_bf16 v[14:17], v[130:133], v[214:217], v[14:17]
	v_mfma_f32_16x16x32_bf16 v[10:13], v[154:157], v[214:217], v[10:13]
	v_mfma_f32_16x16x32_bf16 v[62:65], v[150:153], v[190:193], v[62:65]
	v_mfma_f32_16x16x32_bf16 v[58:61], v[158:161], v[190:193], v[58:61]
	v_mfma_f32_16x16x32_bf16 v[46:49], v[150:153], v[198:201], v[46:49]
	v_mfma_f32_16x16x32_bf16 v[42:45], v[158:161], v[198:201], v[42:45]
	v_mfma_f32_16x16x32_bf16 v[30:33], v[150:153], v[210:213], v[30:33]
	v_mfma_f32_16x16x32_bf16 v[26:29], v[158:161], v[210:213], v[26:29]
	v_mfma_f32_16x16x32_bf16 v[14:17], v[150:153], v[218:221], v[14:17]
	v_mfma_f32_16x16x32_bf16 v[10:13], v[158:161], v[218:221], v[10:13]
	s_setprio 0
	s_setprio 1
	v_mfma_f32_16x16x32_bf16 v[54:57], v[162:165], v[186:189], v[54:57]
	v_mfma_f32_16x16x32_bf16 v[50:53], v[178:181], v[186:189], v[50:53]
	v_mfma_f32_16x16x32_bf16 v[38:41], v[162:165], v[194:197], v[38:41]
	v_mfma_f32_16x16x32_bf16 v[34:37], v[178:181], v[194:197], v[34:37]
	v_mfma_f32_16x16x32_bf16 v[22:25], v[162:165], v[202:205], v[22:25]
	v_mfma_f32_16x16x32_bf16 v[18:21], v[178:181], v[202:205], v[18:21]
	v_mfma_f32_16x16x32_bf16 v[6:9], v[162:165], v[214:217], v[6:9]
	v_mfma_f32_16x16x32_bf16 v[2:5], v[178:181], v[214:217], v[2:5]
	v_mfma_f32_16x16x32_bf16 v[54:57], v[174:177], v[190:193], v[54:57]
	v_mfma_f32_16x16x32_bf16 v[50:53], v[182:185], v[190:193], v[50:53]
	v_mfma_f32_16x16x32_bf16 v[38:41], v[174:177], v[198:201], v[38:41]
	v_mfma_f32_16x16x32_bf16 v[34:37], v[182:185], v[198:201], v[34:37]
	v_mfma_f32_16x16x32_bf16 v[22:25], v[174:177], v[210:213], v[22:25]
	v_mfma_f32_16x16x32_bf16 v[18:21], v[182:185], v[210:213], v[18:21]
	s_setprio 3
	s_barrier
	v_mfma_f32_16x16x32_bf16 v[6:9], v[174:177], v[218:221], v[6:9]
	v_mfma_f32_16x16x32_bf16 v[2:5], v[182:185], v[218:221], v[2:5]
	s_setprio 0
	s_add_u32 s95, s95, 0x100
	s_addc_u32 s96, s96, 0
	s_add_u32 s0, s0, 0x100
	s_addc_u32 s1, s1, 0
	s_cmp_ge_i32 s46, s65
	s_mov_b32 s44, s46
	s_cbranch_scc0 .LBB0_626

.LBB0_1087:
	v_add_u32_e32 v149, s71, v146
	ds_read_b128 v[142:145], v149
	ds_read_b128 v[152:155], v149 offset:1024
	ds_read_b128 v[156:159], v149 offset:2048
	ds_read_b128 v[160:163], v149 offset:3072
	v_add_u32_e32 v149, s72, v146
	ds_read_b128 v[164:167], v149
	ds_read_b128 v[168:171], v149 offset:1024
	ds_read_b128 v[172:175], v149 offset:2048
	ds_read_b128 v[176:179], v149 offset:3072
	s_add_i32 s42, s40, 2
	s_add_u32 s43, s4, 0x80
	s_addc_u32 s41, s5, 0
	s_cmp_eq_u32 s58, s40
	s_cselect_b32 s40, s36, s43
	s_cselect_b32 s41, s37, s41
	s_cselect_b32 s81, s39, s78
	s_cselect_b32 s80, s38, s77
	v_lshl_add_u64 v[214:215], s[4:5], 0, v[140:141]
	s_add_i32 m0, s48, 0xc000
	ds_read_b128 v[180:183], v147
	ds_read_b128 v[184:187], v147 offset:1024
	ds_read_b128 v[188:191], v147 offset:2048
	ds_read_b128 v[192:195], v147 offset:3072
	ds_read_b128 v[196:199], v147 offset:4096
	ds_read_b128 v[200:203], v147 offset:5120
	ds_read_b128 v[204:207], v147 offset:6144
	ds_read_b128 v[210:213], v147 offset:7168
	global_load_lds_dwordx4 v[214:215], off
	v_lshl_add_u64 v[214:215], s[4:5], 0, v[138:139]
	s_add_i32 m0, s48, 0xe000
	s_nop 0
	global_load_lds_dwordx4 v[214:215], off
	s_waitcnt vmcnt(8)
	s_waitcnt lgkmcnt(0)
	s_barrier
	s_setprio 1
	s_waitcnt lgkmcnt(0)
	v_mfma_f32_16x16x32_bf16 v[126:129], v[142:145], v[180:183], v[126:129]
	v_mfma_f32_16x16x32_bf16 v[122:125], v[156:159], v[180:183], v[122:125]
	v_mfma_f32_16x16x32_bf16 v[110:113], v[142:145], v[188:191], v[110:113]
	v_mfma_f32_16x16x32_bf16 v[106:109], v[156:159], v[188:191], v[106:109]
	v_mfma_f32_16x16x32_bf16 v[94:97], v[142:145], v[196:199], v[94:97]
	v_mfma_f32_16x16x32_bf16 v[90:93], v[156:159], v[196:199], v[90:93]
	v_mfma_f32_16x16x32_bf16 v[78:81], v[142:145], v[204:207], v[78:81]
	v_mfma_f32_16x16x32_bf16 v[74:77], v[156:159], v[204:207], v[74:77]
	v_mfma_f32_16x16x32_bf16 v[126:129], v[152:155], v[184:187], v[126:129]
	v_mfma_f32_16x16x32_bf16 v[122:125], v[160:163], v[184:187], v[122:125]
	v_mfma_f32_16x16x32_bf16 v[110:113], v[152:155], v[192:195], v[110:113]
	v_mfma_f32_16x16x32_bf16 v[106:109], v[160:163], v[192:195], v[106:109]
	v_mfma_f32_16x16x32_bf16 v[94:97], v[152:155], v[200:203], v[94:97]
	v_mfma_f32_16x16x32_bf16 v[90:93], v[160:163], v[200:203], v[90:93]
	v_mfma_f32_16x16x32_bf16 v[78:81], v[152:155], v[210:213], v[78:81]
	v_mfma_f32_16x16x32_bf16 v[74:77], v[160:163], v[210:213], v[74:77]
	s_setprio 0
	s_setprio 1
	v_mfma_f32_16x16x32_bf16 v[118:121], v[164:167], v[180:183], v[118:121]
	v_mfma_f32_16x16x32_bf16 v[114:117], v[172:175], v[180:183], v[114:117]
	v_mfma_f32_16x16x32_bf16 v[102:105], v[164:167], v[188:191], v[102:105]
	v_mfma_f32_16x16x32_bf16 v[98:101], v[172:175], v[188:191], v[98:101]
	v_mfma_f32_16x16x32_bf16 v[86:89], v[164:167], v[196:199], v[86:89]
	v_mfma_f32_16x16x32_bf16 v[82:85], v[172:175], v[196:199], v[82:85]
	v_mfma_f32_16x16x32_bf16 v[70:73], v[164:167], v[204:207], v[70:73]
	v_mfma_f32_16x16x32_bf16 v[66:69], v[172:175], v[204:207], v[66:69]
	v_mfma_f32_16x16x32_bf16 v[118:121], v[168:171], v[184:187], v[118:121]
	v_mfma_f32_16x16x32_bf16 v[114:117], v[176:179], v[184:187], v[114:117]
	v_mfma_f32_16x16x32_bf16 v[102:105], v[168:171], v[192:195], v[102:105]
	v_mfma_f32_16x16x32_bf16 v[98:101], v[176:179], v[192:195], v[98:101]
	v_mfma_f32_16x16x32_bf16 v[86:89], v[168:171], v[200:203], v[86:89]
	v_mfma_f32_16x16x32_bf16 v[82:85], v[176:179], v[200:203], v[82:85]
	s_setprio 3
	s_barrier
	v_mfma_f32_16x16x32_bf16 v[70:73], v[168:171], v[210:213], v[70:73]
	v_mfma_f32_16x16x32_bf16 v[66:69], v[176:179], v[210:213], v[66:69]
	s_setprio 0
	s_add_i32 s43, s71, s45
	v_lshl_add_u64 v[214:215], s[80:81], 0, v[130:131]
	s_mov_b32 m0, s43
	ds_read_b128 v[180:183], v147 offset:16384
	ds_read_b128 v[184:187], v147 offset:17408
	ds_read_b128 v[188:191], v147 offset:18432
	ds_read_b128 v[192:195], v147 offset:19456
	ds_read_b128 v[196:199], v147 offset:20480
	ds_read_b128 v[200:203], v147 offset:21504
	ds_read_b128 v[204:207], v147 offset:22528
	ds_read_b128 v[210:213], v147 offset:23552
	global_load_lds_dwordx4 v[214:215], off
	s_add_i32 m0, s43, 0x2000
	v_lshl_add_u64 v[216:217], s[80:81], 0, v[132:133]
	s_add_u32 s80, s80, s12
	s_addc_u32 s81, s81, s13
	s_add_i32 s43, s72, s45
	global_load_lds_dwordx4 v[216:217], off
	v_lshl_add_u64 v[218:219], s[80:81], 0, v[130:131]
	s_mov_b32 m0, s43
	v_lshl_add_u64 v[220:221], s[80:81], 0, v[132:133]
	global_load_lds_dwordx4 v[218:219], off
	s_add_i32 m0, s43, 0x2000
	v_lshl_add_u64 v[222:223], s[40:41], 0, v[134:135]
	global_load_lds_dwordx4 v[220:221], off
	s_mov_b32 m0, s48
	v_lshl_add_u64 v[224:225], s[40:41], 0, v[136:137]
	global_load_lds_dwordx4 v[222:223], off
	s_mov_b32 m0, s49
	s_nop 0
	global_load_lds_dwordx4 v[224:225], off
	s_waitcnt vmcnt(8)
	s_waitcnt lgkmcnt(0)
	s_barrier
	s_setprio 1
	s_waitcnt lgkmcnt(0)
	v_mfma_f32_16x16x32_bf16 v[62:65], v[142:145], v[180:183], v[62:65]
	v_mfma_f32_16x16x32_bf16 v[58:61], v[156:159], v[180:183], v[58:61]
	v_mfma_f32_16x16x32_bf16 v[46:49], v[142:145], v[188:191], v[46:49]
	v_mfma_f32_16x16x32_bf16 v[42:45], v[156:159], v[188:191], v[42:45]
	v_mfma_f32_16x16x32_bf16 v[30:33], v[142:145], v[196:199], v[30:33]
	v_mfma_f32_16x16x32_bf16 v[26:29], v[156:159], v[196:199], v[26:29]
	v_mfma_f32_16x16x32_bf16 v[14:17], v[142:145], v[204:207], v[14:17]
	v_mfma_f32_16x16x32_bf16 v[10:13], v[156:159], v[204:207], v[10:13]
	v_mfma_f32_16x16x32_bf16 v[62:65], v[152:155], v[184:187], v[62:65]
	v_mfma_f32_16x16x32_bf16 v[58:61], v[160:163], v[184:187], v[58:61]
	v_mfma_f32_16x16x32_bf16 v[46:49], v[152:155], v[192:195], v[46:49]
	v_mfma_f32_16x16x32_bf16 v[42:45], v[160:163], v[192:195], v[42:45]
	v_mfma_f32_16x16x32_bf16 v[30:33], v[152:155], v[200:203], v[30:33]
	v_mfma_f32_16x16x32_bf16 v[26:29], v[160:163], v[200:203], v[26:29]
	v_mfma_f32_16x16x32_bf16 v[14:17], v[152:155], v[210:213], v[14:17]
	v_mfma_f32_16x16x32_bf16 v[10:13], v[160:163], v[210:213], v[10:13]
	s_setprio 0
	s_setprio 1
	v_mfma_f32_16x16x32_bf16 v[54:57], v[164:167], v[180:183], v[54:57]
	v_mfma_f32_16x16x32_bf16 v[50:53], v[172:175], v[180:183], v[50:53]
	v_mfma_f32_16x16x32_bf16 v[38:41], v[164:167], v[188:191], v[38:41]
	v_mfma_f32_16x16x32_bf16 v[34:37], v[172:175], v[188:191], v[34:37]
	v_mfma_f32_16x16x32_bf16 v[22:25], v[164:167], v[196:199], v[22:25]
	v_mfma_f32_16x16x32_bf16 v[18:21], v[172:175], v[196:199], v[18:21]
	v_mfma_f32_16x16x32_bf16 v[6:9], v[164:167], v[204:207], v[6:9]
	v_mfma_f32_16x16x32_bf16 v[2:5], v[172:175], v[204:207], v[2:5]
	v_mfma_f32_16x16x32_bf16 v[54:57], v[168:171], v[184:187], v[54:57]
	v_mfma_f32_16x16x32_bf16 v[50:53], v[176:179], v[184:187], v[50:53]
	v_mfma_f32_16x16x32_bf16 v[38:41], v[168:171], v[192:195], v[38:41]
	v_mfma_f32_16x16x32_bf16 v[34:37], v[176:179], v[192:195], v[34:37]
	v_mfma_f32_16x16x32_bf16 v[22:25], v[168:171], v[200:203], v[22:25]
	v_mfma_f32_16x16x32_bf16 v[18:21], v[176:179], v[200:203], v[18:21]
	s_setprio 3
	s_barrier
	v_mfma_f32_16x16x32_bf16 v[6:9], v[168:171], v[210:213], v[6:9]
	v_mfma_f32_16x16x32_bf16 v[2:5], v[176:179], v[210:213], v[2:5]
	s_setprio 0
	s_add_i32 s43, 0, 0x18000
	v_add_u32_e32 v149, s43, v146
	s_add_i32 s79, 0, 0x1c000
	ds_read_b128 v[142:145], v149
	ds_read_b128 v[152:155], v149 offset:1024
	ds_read_b128 v[156:159], v149 offset:2048
	ds_read_b128 v[160:163], v149 offset:3072
	v_add_u32_e32 v149, s79, v146
	ds_read_b128 v[164:167], v149
	ds_read_b128 v[168:171], v149 offset:1024
	ds_read_b128 v[172:175], v149 offset:2048
	ds_read_b128 v[176:179], v149 offset:3072
	s_add_u32 s40, s40, s12
	s_addc_u32 s41, s41, s13
	s_mov_b32 m0, s50
	v_lshl_add_u64 v[226:227], s[40:41], 0, v[134:135]
	ds_read_b128 v[180:183], v147 offset:32768
	ds_read_b128 v[184:187], v147 offset:33792
	ds_read_b128 v[188:191], v147 offset:34816
	ds_read_b128 v[192:195], v147 offset:35840
	ds_read_b128 v[196:199], v147 offset:36864
	ds_read_b128 v[200:203], v147 offset:37888
	ds_read_b128 v[204:207], v147 offset:38912
	ds_read_b128 v[210:213], v147 offset:39936
	global_load_lds_dwordx4 v[226:227], off
	v_lshl_add_u64 v[226:227], s[40:41], 0, v[136:137]
	s_mov_b32 m0, s51
	s_nop 0
	global_load_lds_dwordx4 v[226:227], off
	s_waitcnt vmcnt(8)
	s_waitcnt lgkmcnt(0)
	s_barrier
	s_setprio 1
	s_waitcnt lgkmcnt(0)
	v_mfma_f32_16x16x32_bf16 v[126:129], v[142:145], v[180:183], v[126:129]
	v_mfma_f32_16x16x32_bf16 v[122:125], v[156:159], v[180:183], v[122:125]
	v_mfma_f32_16x16x32_bf16 v[110:113], v[142:145], v[188:191], v[110:113]
	v_mfma_f32_16x16x32_bf16 v[106:109], v[156:159], v[188:191], v[106:109]
	v_mfma_f32_16x16x32_bf16 v[94:97], v[142:145], v[196:199], v[94:97]
	v_mfma_f32_16x16x32_bf16 v[90:93], v[156:159], v[196:199], v[90:93]
	v_mfma_f32_16x16x32_bf16 v[78:81], v[142:145], v[204:207], v[78:81]
	v_mfma_f32_16x16x32_bf16 v[74:77], v[156:159], v[204:207], v[74:77]
	v_mfma_f32_16x16x32_bf16 v[126:129], v[152:155], v[184:187], v[126:129]
	v_mfma_f32_16x16x32_bf16 v[122:125], v[160:163], v[184:187], v[122:125]
	v_mfma_f32_16x16x32_bf16 v[110:113], v[152:155], v[192:195], v[110:113]
	v_mfma_f32_16x16x32_bf16 v[106:109], v[160:163], v[192:195], v[106:109]
	v_mfma_f32_16x16x32_bf16 v[94:97], v[152:155], v[200:203], v[94:97]
	v_mfma_f32_16x16x32_bf16 v[90:93], v[160:163], v[200:203], v[90:93]
	v_mfma_f32_16x16x32_bf16 v[78:81], v[152:155], v[210:213], v[78:81]
	v_mfma_f32_16x16x32_bf16 v[74:77], v[160:163], v[210:213], v[74:77]
	s_setprio 0
	s_setprio 1
	v_mfma_f32_16x16x32_bf16 v[118:121], v[164:167], v[180:183], v[118:121]
	v_mfma_f32_16x16x32_bf16 v[114:117], v[172:175], v[180:183], v[114:117]
	v_mfma_f32_16x16x32_bf16 v[102:105], v[164:167], v[188:191], v[102:105]
	v_mfma_f32_16x16x32_bf16 v[98:101], v[172:175], v[188:191], v[98:101]
	v_mfma_f32_16x16x32_bf16 v[86:89], v[164:167], v[196:199], v[86:89]
	v_mfma_f32_16x16x32_bf16 v[82:85], v[172:175], v[196:199], v[82:85]
	v_mfma_f32_16x16x32_bf16 v[70:73], v[164:167], v[204:207], v[70:73]
	v_mfma_f32_16x16x32_bf16 v[66:69], v[172:175], v[204:207], v[66:69]
	v_mfma_f32_16x16x32_bf16 v[118:121], v[168:171], v[184:187], v[118:121]
	v_mfma_f32_16x16x32_bf16 v[114:117], v[176:179], v[184:187], v[114:117]
	v_mfma_f32_16x16x32_bf16 v[102:105], v[168:171], v[192:195], v[102:105]
	v_mfma_f32_16x16x32_bf16 v[98:101], v[176:179], v[192:195], v[98:101]
	v_mfma_f32_16x16x32_bf16 v[86:89], v[168:171], v[200:203], v[86:89]
	v_mfma_f32_16x16x32_bf16 v[82:85], v[176:179], v[200:203], v[82:85]
	s_setprio 3
	s_barrier
	v_mfma_f32_16x16x32_bf16 v[70:73], v[168:171], v[210:213], v[70:73]
	v_mfma_f32_16x16x32_bf16 v[66:69], v[176:179], v[210:213], v[66:69]
	s_setprio 0
	s_add_i32 s40, s43, s45
	v_lshl_add_u64 v[214:215], v[214:215], 0, s[20:21]
	s_mov_b32 m0, s40
	ds_read_b128 v[180:183], v147 offset:49152
	ds_read_b128 v[184:187], v147 offset:50176
	ds_read_b128 v[188:191], v147 offset:51200
	ds_read_b128 v[192:195], v147 offset:52224
	ds_read_b128 v[196:199], v147 offset:53248
	ds_read_b128 v[200:203], v147 offset:54272
	ds_read_b128 v[204:207], v147 offset:55296
	ds_read_b128 v[210:213], v147 offset:56320
	global_load_lds_dwordx4 v[214:215], off
	v_lshl_add_u64 v[214:215], v[216:217], 0, s[20:21]
	s_add_i32 m0, s40, 0x2000
	s_add_i32 s40, s79, s45
	global_load_lds_dwordx4 v[214:215], off
	v_lshl_add_u64 v[214:215], v[218:219], 0, s[20:21]
	s_mov_b32 m0, s40
	s_nop 0
	global_load_lds_dwordx4 v[214:215], off
	v_lshl_add_u64 v[214:215], v[220:221], 0, s[20:21]
	s_add_i32 m0, s40, 0x2000
	s_nop 0
	global_load_lds_dwordx4 v[214:215], off
	v_lshl_add_u64 v[214:215], v[222:223], 0, s[20:21]
	s_mov_b32 m0, s56
	s_nop 0
	global_load_lds_dwordx4 v[214:215], off
	v_lshl_add_u64 v[214:215], v[224:225], 0, s[20:21]
	s_mov_b32 m0, s57
	s_nop 0
	global_load_lds_dwordx4 v[214:215], off
	s_waitcnt vmcnt(8)
	s_waitcnt lgkmcnt(0)
	s_barrier
	s_setprio 1
	s_waitcnt lgkmcnt(0)
	v_mfma_f32_16x16x32_bf16 v[62:65], v[142:145], v[180:183], v[62:65]
	v_mfma_f32_16x16x32_bf16 v[58:61], v[156:159], v[180:183], v[58:61]
	v_mfma_f32_16x16x32_bf16 v[46:49], v[142:145], v[188:191], v[46:49]
	v_mfma_f32_16x16x32_bf16 v[42:45], v[156:159], v[188:191], v[42:45]
	v_mfma_f32_16x16x32_bf16 v[30:33], v[142:145], v[196:199], v[30:33]
	v_mfma_f32_16x16x32_bf16 v[26:29], v[156:159], v[196:199], v[26:29]
	v_mfma_f32_16x16x32_bf16 v[14:17], v[142:145], v[204:207], v[14:17]
	v_mfma_f32_16x16x32_bf16 v[10:13], v[156:159], v[204:207], v[10:13]
	v_mfma_f32_16x16x32_bf16 v[62:65], v[152:155], v[184:187], v[62:65]
	v_mfma_f32_16x16x32_bf16 v[58:61], v[160:163], v[184:187], v[58:61]
	v_mfma_f32_16x16x32_bf16 v[46:49], v[152:155], v[192:195], v[46:49]
	v_mfma_f32_16x16x32_bf16 v[42:45], v[160:163], v[192:195], v[42:45]
	v_mfma_f32_16x16x32_bf16 v[30:33], v[152:155], v[200:203], v[30:33]
	v_mfma_f32_16x16x32_bf16 v[26:29], v[160:163], v[200:203], v[26:29]
	v_mfma_f32_16x16x32_bf16 v[14:17], v[152:155], v[210:213], v[14:17]
	v_mfma_f32_16x16x32_bf16 v[10:13], v[160:163], v[210:213], v[10:13]
	s_setprio 0
	s_setprio 1
	v_mfma_f32_16x16x32_bf16 v[54:57], v[164:167], v[180:183], v[54:57]
	v_mfma_f32_16x16x32_bf16 v[50:53], v[172:175], v[180:183], v[50:53]
	v_mfma_f32_16x16x32_bf16 v[38:41], v[164:167], v[188:191], v[38:41]
	v_mfma_f32_16x16x32_bf16 v[34:37], v[172:175], v[188:191], v[34:37]
	v_mfma_f32_16x16x32_bf16 v[22:25], v[164:167], v[196:199], v[22:25]
	v_mfma_f32_16x16x32_bf16 v[18:21], v[172:175], v[196:199], v[18:21]
	v_mfma_f32_16x16x32_bf16 v[6:9], v[164:167], v[204:207], v[6:9]
	v_mfma_f32_16x16x32_bf16 v[2:5], v[172:175], v[204:207], v[2:5]
	v_mfma_f32_16x16x32_bf16 v[54:57], v[168:171], v[184:187], v[54:57]
	v_mfma_f32_16x16x32_bf16 v[50:53], v[176:179], v[184:187], v[50:53]
	v_mfma_f32_16x16x32_bf16 v[38:41], v[168:171], v[192:195], v[38:41]
	v_mfma_f32_16x16x32_bf16 v[34:37], v[176:179], v[192:195], v[34:37]
	v_mfma_f32_16x16x32_bf16 v[22:25], v[168:171], v[200:203], v[22:25]
	v_mfma_f32_16x16x32_bf16 v[18:21], v[176:179], v[200:203], v[18:21]
	s_setprio 3
	s_barrier
	v_mfma_f32_16x16x32_bf16 v[6:9], v[168:171], v[210:213], v[6:9]
	v_mfma_f32_16x16x32_bf16 v[2:5], v[176:179], v[210:213], v[2:5]
	s_setprio 0
	s_add_u32 s77, s77, 0x100
	s_addc_u32 s78, s78, 0
	s_add_u32 s4, s4, 0x100
	s_addc_u32 s5, s5, 0
	s_cmp_ge_i32 s42, s55
	s_mov_b32 s40, s42
	s_cbranch_scc0 .LBB0_1087

.LBB0_1199:
	ds_read_b128 v[144:147], v153
	ds_read_b128 v[158:161], v153 offset:1024
	ds_read_b128 v[162:165], v153 offset:2048
	ds_read_b128 v[166:169], v153 offset:3072
	ds_read_b128 v[170:173], v154
	ds_read_b128 v[174:177], v154 offset:1024
	ds_read_b128 v[178:181], v154 offset:2048
	ds_read_b128 v[182:185], v154 offset:3072
	s_add_i32 s74, s38, 2
	s_add_u32 s75, s36, 0x80
	s_addc_u32 s39, s37, 0
	s_cmp_eq_u32 s61, s38
	s_cselect_b32 s38, s4, s75
	s_cselect_b32 s39, s5, s39
	s_cselect_b32 s77, s25, s73
	s_cselect_b32 s76, s24, s72
	v_lshl_add_u64 v[148:149], s[36:37], 0, v[140:141]
	s_add_i32 m0, s51, 0xc000
	ds_read_b128 v[186:189], v155
	ds_read_b128 v[190:193], v155 offset:1024
	ds_read_b128 v[194:197], v155 offset:2048
	ds_read_b128 v[198:201], v155 offset:3072
	ds_read_b128 v[202:205], v155 offset:4096
	ds_read_b128 v[210:213], v155 offset:5120
	ds_read_b128 v[214:217], v155 offset:6144
	ds_read_b128 v[218:221], v155 offset:7168
	global_load_lds_dwordx4 v[148:149], off
	v_lshl_add_u64 v[148:149], s[36:37], 0, v[138:139]
	s_add_i32 m0, s51, 0xe000
	s_nop 0
	global_load_lds_dwordx4 v[148:149], off
	s_waitcnt vmcnt(8)
	s_waitcnt lgkmcnt(0)
	s_barrier
	s_setprio 1
	s_waitcnt lgkmcnt(0)
	v_mfma_f32_16x16x32_bf16 v[122:125], v[144:147], v[186:189], v[122:125]
	v_mfma_f32_16x16x32_bf16 v[126:129], v[162:165], v[186:189], v[126:129]
	v_mfma_f32_16x16x32_bf16 v[110:113], v[144:147], v[194:197], v[110:113]
	v_mfma_f32_16x16x32_bf16 v[106:109], v[162:165], v[194:197], v[106:109]
	v_mfma_f32_16x16x32_bf16 v[94:97], v[144:147], v[202:205], v[94:97]
	v_mfma_f32_16x16x32_bf16 v[90:93], v[162:165], v[202:205], v[90:93]
	v_mfma_f32_16x16x32_bf16 v[78:81], v[144:147], v[214:217], v[78:81]
	v_mfma_f32_16x16x32_bf16 v[74:77], v[162:165], v[214:217], v[74:77]
	v_mfma_f32_16x16x32_bf16 v[122:125], v[158:161], v[190:193], v[122:125]
	v_mfma_f32_16x16x32_bf16 v[126:129], v[166:169], v[190:193], v[126:129]
	v_mfma_f32_16x16x32_bf16 v[110:113], v[158:161], v[198:201], v[110:113]
	v_mfma_f32_16x16x32_bf16 v[106:109], v[166:169], v[198:201], v[106:109]
	v_mfma_f32_16x16x32_bf16 v[94:97], v[158:161], v[210:213], v[94:97]
	v_mfma_f32_16x16x32_bf16 v[90:93], v[166:169], v[210:213], v[90:93]
	v_mfma_f32_16x16x32_bf16 v[78:81], v[158:161], v[218:221], v[78:81]
	v_mfma_f32_16x16x32_bf16 v[74:77], v[166:169], v[218:221], v[74:77]
	s_setprio 0
	s_setprio 1
	v_mfma_f32_16x16x32_bf16 v[118:121], v[170:173], v[186:189], v[118:121]
	v_mfma_f32_16x16x32_bf16 v[114:117], v[178:181], v[186:189], v[114:117]
	v_mfma_f32_16x16x32_bf16 v[102:105], v[170:173], v[194:197], v[102:105]
	v_mfma_f32_16x16x32_bf16 v[98:101], v[178:181], v[194:197], v[98:101]
	v_mfma_f32_16x16x32_bf16 v[86:89], v[170:173], v[202:205], v[86:89]
	v_mfma_f32_16x16x32_bf16 v[82:85], v[178:181], v[202:205], v[82:85]
	v_mfma_f32_16x16x32_bf16 v[70:73], v[170:173], v[214:217], v[70:73]
	v_mfma_f32_16x16x32_bf16 v[66:69], v[178:181], v[214:217], v[66:69]
	v_mfma_f32_16x16x32_bf16 v[118:121], v[174:177], v[190:193], v[118:121]
	v_mfma_f32_16x16x32_bf16 v[114:117], v[182:185], v[190:193], v[114:117]
	v_mfma_f32_16x16x32_bf16 v[102:105], v[174:177], v[198:201], v[102:105]
	v_mfma_f32_16x16x32_bf16 v[98:101], v[182:185], v[198:201], v[98:101]
	v_mfma_f32_16x16x32_bf16 v[86:89], v[174:177], v[210:213], v[86:89]
	v_mfma_f32_16x16x32_bf16 v[82:85], v[182:185], v[210:213], v[82:85]
	s_setprio 3
	s_barrier
	v_mfma_f32_16x16x32_bf16 v[70:73], v[174:177], v[218:221], v[70:73]
	v_mfma_f32_16x16x32_bf16 v[66:69], v[182:185], v[218:221], v[66:69]
	s_setprio 0
	s_add_i32 s75, s63, s48
	v_lshl_add_u64 v[148:149], s[76:77], 0, v[130:131]
	s_mov_b32 m0, s75
	ds_read_b128 v[186:189], v155 offset:16384
	ds_read_b128 v[190:193], v155 offset:17408
	ds_read_b128 v[194:197], v155 offset:18432
	ds_read_b128 v[198:201], v155 offset:19456
	ds_read_b128 v[202:205], v155 offset:20480
	ds_read_b128 v[210:213], v155 offset:21504
	ds_read_b128 v[214:217], v155 offset:22528
	ds_read_b128 v[218:221], v155 offset:23552
	global_load_lds_dwordx4 v[148:149], off
	s_add_i32 m0, s75, 0x2000
	v_lshl_add_u64 v[206:207], s[76:77], 0, v[132:133]
	s_add_u32 s76, s76, s10
	s_addc_u32 s77, s77, s11
	s_add_i32 s75, s64, s48
	global_load_lds_dwordx4 v[206:207], off
	v_lshl_add_u64 v[222:223], s[76:77], 0, v[130:131]
	s_mov_b32 m0, s75
	v_lshl_add_u64 v[224:225], s[76:77], 0, v[132:133]
	global_load_lds_dwordx4 v[222:223], off
	s_add_i32 m0, s75, 0x2000
	v_lshl_add_u64 v[226:227], s[38:39], 0, v[134:135]
	global_load_lds_dwordx4 v[224:225], off
	s_mov_b32 m0, s51
	v_lshl_add_u64 v[228:229], s[38:39], 0, v[136:137]
	global_load_lds_dwordx4 v[226:227], off
	s_mov_b32 m0, s52
	s_nop 0
	global_load_lds_dwordx4 v[228:229], off
	s_waitcnt vmcnt(8)
	s_waitcnt lgkmcnt(0)
	s_barrier
	s_setprio 1
	s_waitcnt lgkmcnt(0)
	v_mfma_f32_16x16x32_bf16 v[62:65], v[144:147], v[186:189], v[62:65]
	v_mfma_f32_16x16x32_bf16 v[58:61], v[162:165], v[186:189], v[58:61]
	v_mfma_f32_16x16x32_bf16 v[46:49], v[144:147], v[194:197], v[46:49]
	v_mfma_f32_16x16x32_bf16 v[42:45], v[162:165], v[194:197], v[42:45]
	v_mfma_f32_16x16x32_bf16 v[30:33], v[144:147], v[202:205], v[30:33]
	v_mfma_f32_16x16x32_bf16 v[26:29], v[162:165], v[202:205], v[26:29]
	v_mfma_f32_16x16x32_bf16 v[14:17], v[144:147], v[214:217], v[14:17]
	v_mfma_f32_16x16x32_bf16 v[10:13], v[162:165], v[214:217], v[10:13]
	v_mfma_f32_16x16x32_bf16 v[62:65], v[158:161], v[190:193], v[62:65]
	v_mfma_f32_16x16x32_bf16 v[58:61], v[166:169], v[190:193], v[58:61]
	v_mfma_f32_16x16x32_bf16 v[46:49], v[158:161], v[198:201], v[46:49]
	v_mfma_f32_16x16x32_bf16 v[42:45], v[166:169], v[198:201], v[42:45]
	v_mfma_f32_16x16x32_bf16 v[30:33], v[158:161], v[210:213], v[30:33]
	v_mfma_f32_16x16x32_bf16 v[26:29], v[166:169], v[210:213], v[26:29]
	v_mfma_f32_16x16x32_bf16 v[14:17], v[158:161], v[218:221], v[14:17]
	v_mfma_f32_16x16x32_bf16 v[10:13], v[166:169], v[218:221], v[10:13]
	s_setprio 0
	s_setprio 1
	v_mfma_f32_16x16x32_bf16 v[54:57], v[170:173], v[186:189], v[54:57]
	v_mfma_f32_16x16x32_bf16 v[50:53], v[178:181], v[186:189], v[50:53]
	v_mfma_f32_16x16x32_bf16 v[38:41], v[170:173], v[194:197], v[38:41]
	v_mfma_f32_16x16x32_bf16 v[34:37], v[178:181], v[194:197], v[34:37]
	v_mfma_f32_16x16x32_bf16 v[22:25], v[170:173], v[202:205], v[22:25]
	v_mfma_f32_16x16x32_bf16 v[18:21], v[178:181], v[202:205], v[18:21]
	v_mfma_f32_16x16x32_bf16 v[6:9], v[170:173], v[214:217], v[6:9]
	v_mfma_f32_16x16x32_bf16 v[2:5], v[178:181], v[214:217], v[2:5]
	v_mfma_f32_16x16x32_bf16 v[54:57], v[174:177], v[190:193], v[54:57]
	v_mfma_f32_16x16x32_bf16 v[50:53], v[182:185], v[190:193], v[50:53]
	v_mfma_f32_16x16x32_bf16 v[38:41], v[174:177], v[198:201], v[38:41]
	v_mfma_f32_16x16x32_bf16 v[34:37], v[182:185], v[198:201], v[34:37]
	v_mfma_f32_16x16x32_bf16 v[22:25], v[174:177], v[210:213], v[22:25]
	v_mfma_f32_16x16x32_bf16 v[18:21], v[182:185], v[210:213], v[18:21]
	s_setprio 3
	s_barrier
	v_mfma_f32_16x16x32_bf16 v[6:9], v[174:177], v[218:221], v[6:9]
	v_mfma_f32_16x16x32_bf16 v[2:5], v[182:185], v[218:221], v[2:5]
	s_setprio 0
	s_add_i32 s75, 0, 0x18000
	v_add_u32_e32 v157, s75, v152
	s_add_i32 s76, 0, 0x1c000
	ds_read_b128 v[144:147], v157
	ds_read_b128 v[158:161], v157 offset:1024
	ds_read_b128 v[162:165], v157 offset:2048
	ds_read_b128 v[166:169], v157 offset:3072
	v_add_u32_e32 v157, s76, v152
	ds_read_b128 v[170:173], v157
	ds_read_b128 v[174:177], v157 offset:1024
	ds_read_b128 v[178:181], v157 offset:2048
	ds_read_b128 v[182:185], v157 offset:3072
	s_add_u32 s38, s38, s10
	s_addc_u32 s39, s39, s11
	s_mov_b32 m0, s53
	v_lshl_add_u64 v[230:231], s[38:39], 0, v[134:135]
	ds_read_b128 v[186:189], v155 offset:32768
	ds_read_b128 v[190:193], v155 offset:33792
	ds_read_b128 v[194:197], v155 offset:34816
	ds_read_b128 v[198:201], v155 offset:35840
	ds_read_b128 v[202:205], v155 offset:36864
	ds_read_b128 v[210:213], v155 offset:37888
	ds_read_b128 v[214:217], v155 offset:38912
	ds_read_b128 v[218:221], v155 offset:39936
	global_load_lds_dwordx4 v[230:231], off
	v_lshl_add_u64 v[230:231], s[38:39], 0, v[136:137]
	s_mov_b32 m0, s54
	s_nop 0
	global_load_lds_dwordx4 v[230:231], off
	s_waitcnt vmcnt(8)
	s_waitcnt lgkmcnt(0)
	s_barrier
	s_setprio 1
	s_waitcnt lgkmcnt(0)
	v_mfma_f32_16x16x32_bf16 v[122:125], v[144:147], v[186:189], v[122:125]
	v_mfma_f32_16x16x32_bf16 v[126:129], v[162:165], v[186:189], v[126:129]
	v_mfma_f32_16x16x32_bf16 v[110:113], v[144:147], v[194:197], v[110:113]
	v_mfma_f32_16x16x32_bf16 v[106:109], v[162:165], v[194:197], v[106:109]
	v_mfma_f32_16x16x32_bf16 v[94:97], v[144:147], v[202:205], v[94:97]
	v_mfma_f32_16x16x32_bf16 v[90:93], v[162:165], v[202:205], v[90:93]
	v_mfma_f32_16x16x32_bf16 v[78:81], v[144:147], v[214:217], v[78:81]
	v_mfma_f32_16x16x32_bf16 v[74:77], v[162:165], v[214:217], v[74:77]
	v_mfma_f32_16x16x32_bf16 v[122:125], v[158:161], v[190:193], v[122:125]
	v_mfma_f32_16x16x32_bf16 v[126:129], v[166:169], v[190:193], v[126:129]
	v_mfma_f32_16x16x32_bf16 v[110:113], v[158:161], v[198:201], v[110:113]
	v_mfma_f32_16x16x32_bf16 v[106:109], v[166:169], v[198:201], v[106:109]
	v_mfma_f32_16x16x32_bf16 v[94:97], v[158:161], v[210:213], v[94:97]
	v_mfma_f32_16x16x32_bf16 v[90:93], v[166:169], v[210:213], v[90:93]
	v_mfma_f32_16x16x32_bf16 v[78:81], v[158:161], v[218:221], v[78:81]
	v_mfma_f32_16x16x32_bf16 v[74:77], v[166:169], v[218:221], v[74:77]
	s_setprio 0
	s_setprio 1
	v_mfma_f32_16x16x32_bf16 v[118:121], v[170:173], v[186:189], v[118:121]
	v_mfma_f32_16x16x32_bf16 v[114:117], v[178:181], v[186:189], v[114:117]
	v_mfma_f32_16x16x32_bf16 v[102:105], v[170:173], v[194:197], v[102:105]
	v_mfma_f32_16x16x32_bf16 v[98:101], v[178:181], v[194:197], v[98:101]
	v_mfma_f32_16x16x32_bf16 v[86:89], v[170:173], v[202:205], v[86:89]
	v_mfma_f32_16x16x32_bf16 v[82:85], v[178:181], v[202:205], v[82:85]
	v_mfma_f32_16x16x32_bf16 v[70:73], v[170:173], v[214:217], v[70:73]
	v_mfma_f32_16x16x32_bf16 v[66:69], v[178:181], v[214:217], v[66:69]
	v_mfma_f32_16x16x32_bf16 v[118:121], v[174:177], v[190:193], v[118:121]
	v_mfma_f32_16x16x32_bf16 v[114:117], v[182:185], v[190:193], v[114:117]
	v_mfma_f32_16x16x32_bf16 v[102:105], v[174:177], v[198:201], v[102:105]
	v_mfma_f32_16x16x32_bf16 v[98:101], v[182:185], v[198:201], v[98:101]
	v_mfma_f32_16x16x32_bf16 v[86:89], v[174:177], v[210:213], v[86:89]
	v_mfma_f32_16x16x32_bf16 v[82:85], v[182:185], v[210:213], v[82:85]
	s_setprio 3
	s_barrier
	v_mfma_f32_16x16x32_bf16 v[70:73], v[174:177], v[218:221], v[70:73]
	v_mfma_f32_16x16x32_bf16 v[66:69], v[182:185], v[218:221], v[66:69]
	s_setprio 0
	s_add_i32 s38, s75, s48
	v_lshl_add_u64 v[148:149], v[148:149], 0, s[18:19]
	s_mov_b32 m0, s38
	ds_read_b128 v[186:189], v155 offset:49152
	ds_read_b128 v[190:193], v155 offset:50176
	ds_read_b128 v[194:197], v155 offset:51200
	ds_read_b128 v[198:201], v155 offset:52224
	ds_read_b128 v[202:205], v155 offset:53248
	ds_read_b128 v[210:213], v155 offset:54272
	ds_read_b128 v[214:217], v155 offset:55296
	ds_read_b128 v[218:221], v155 offset:56320
	global_load_lds_dwordx4 v[148:149], off
	v_lshl_add_u64 v[148:149], v[206:207], 0, s[18:19]
	s_add_i32 m0, s38, 0x2000
	s_add_i32 s38, s76, s48
	global_load_lds_dwordx4 v[148:149], off
	v_lshl_add_u64 v[148:149], v[222:223], 0, s[18:19]
	s_mov_b32 m0, s38
	s_nop 0
	global_load_lds_dwordx4 v[148:149], off
	v_lshl_add_u64 v[148:149], v[224:225], 0, s[18:19]
	s_add_i32 m0, s38, 0x2000
	s_nop 0
	global_load_lds_dwordx4 v[148:149], off
	v_lshl_add_u64 v[148:149], v[226:227], 0, s[18:19]
	s_mov_b32 m0, s57
	s_nop 0
	global_load_lds_dwordx4 v[148:149], off
	v_lshl_add_u64 v[148:149], v[228:229], 0, s[18:19]
	s_mov_b32 m0, s58
	s_nop 0
	global_load_lds_dwordx4 v[148:149], off
	s_waitcnt vmcnt(8)
	s_waitcnt lgkmcnt(0)
	s_barrier
	s_setprio 1
	s_waitcnt lgkmcnt(0)
	v_mfma_f32_16x16x32_bf16 v[62:65], v[144:147], v[186:189], v[62:65]
	v_mfma_f32_16x16x32_bf16 v[58:61], v[162:165], v[186:189], v[58:61]
	v_mfma_f32_16x16x32_bf16 v[46:49], v[144:147], v[194:197], v[46:49]
	v_mfma_f32_16x16x32_bf16 v[42:45], v[162:165], v[194:197], v[42:45]
	v_mfma_f32_16x16x32_bf16 v[30:33], v[144:147], v[202:205], v[30:33]
	v_mfma_f32_16x16x32_bf16 v[26:29], v[162:165], v[202:205], v[26:29]
	v_mfma_f32_16x16x32_bf16 v[14:17], v[144:147], v[214:217], v[14:17]
	v_mfma_f32_16x16x32_bf16 v[10:13], v[162:165], v[214:217], v[10:13]
	v_mfma_f32_16x16x32_bf16 v[62:65], v[158:161], v[190:193], v[62:65]
	v_mfma_f32_16x16x32_bf16 v[58:61], v[166:169], v[190:193], v[58:61]
	v_mfma_f32_16x16x32_bf16 v[46:49], v[158:161], v[198:201], v[46:49]
	v_mfma_f32_16x16x32_bf16 v[42:45], v[166:169], v[198:201], v[42:45]
	v_mfma_f32_16x16x32_bf16 v[30:33], v[158:161], v[210:213], v[30:33]
	v_mfma_f32_16x16x32_bf16 v[26:29], v[166:169], v[210:213], v[26:29]
	v_mfma_f32_16x16x32_bf16 v[14:17], v[158:161], v[218:221], v[14:17]
	v_mfma_f32_16x16x32_bf16 v[10:13], v[166:169], v[218:221], v[10:13]
	s_setprio 0
	s_setprio 1
	v_mfma_f32_16x16x32_bf16 v[54:57], v[170:173], v[186:189], v[54:57]
	v_mfma_f32_16x16x32_bf16 v[50:53], v[178:181], v[186:189], v[50:53]
	v_mfma_f32_16x16x32_bf16 v[38:41], v[170:173], v[194:197], v[38:41]
	v_mfma_f32_16x16x32_bf16 v[34:37], v[178:181], v[194:197], v[34:37]
	v_mfma_f32_16x16x32_bf16 v[22:25], v[170:173], v[202:205], v[22:25]
	v_mfma_f32_16x16x32_bf16 v[18:21], v[178:181], v[202:205], v[18:21]
	v_mfma_f32_16x16x32_bf16 v[6:9], v[170:173], v[214:217], v[6:9]
	v_mfma_f32_16x16x32_bf16 v[2:5], v[178:181], v[214:217], v[2:5]
	v_mfma_f32_16x16x32_bf16 v[54:57], v[174:177], v[190:193], v[54:57]
	v_mfma_f32_16x16x32_bf16 v[50:53], v[182:185], v[190:193], v[50:53]
	v_mfma_f32_16x16x32_bf16 v[38:41], v[174:177], v[198:201], v[38:41]
	v_mfma_f32_16x16x32_bf16 v[34:37], v[182:185], v[198:201], v[34:37]
	v_mfma_f32_16x16x32_bf16 v[22:25], v[174:177], v[210:213], v[22:25]
	v_mfma_f32_16x16x32_bf16 v[18:21], v[182:185], v[210:213], v[18:21]
	s_setprio 3
	s_barrier
	v_mfma_f32_16x16x32_bf16 v[6:9], v[174:177], v[218:221], v[6:9]
	v_mfma_f32_16x16x32_bf16 v[2:5], v[182:185], v[218:221], v[2:5]
	s_setprio 0
	s_add_u32 s72, s72, 0x100
	s_addc_u32 s73, s73, 0
	s_add_u32 s36, s36, 0x100
	s_addc_u32 s37, s37, 0
	s_cmp_ge_i32 s74, s56
	s_mov_b32 s38, s74
	s_cbranch_scc0 .LBB0_1199

.LBB0_1297:
	v_add_u32_e32 v149, s67, v146
	ds_read_b128 v[142:145], v149
	ds_read_b128 v[152:155], v149 offset:1024
	ds_read_b128 v[156:159], v149 offset:2048
	ds_read_b128 v[160:163], v149 offset:3072
	v_add_u32_e32 v149, s70, v146
	ds_read_b128 v[164:167], v149
	ds_read_b128 v[168:171], v149 offset:1024
	ds_read_b128 v[172:175], v149 offset:2048
	ds_read_b128 v[176:179], v149 offset:3072
	s_add_i32 s42, s40, 2
	s_add_u32 s43, s4, 0x80
	s_addc_u32 s41, s5, 0
	s_cmp_eq_u32 s56, s40
	s_cselect_b32 s40, s36, s43
	s_cselect_b32 s41, s37, s41
	s_cselect_b32 s79, s39, s76
	s_cselect_b32 s78, s38, s75
	v_lshl_add_u64 v[214:215], s[4:5], 0, v[140:141]
	s_add_i32 m0, s48, 0xc000
	ds_read_b128 v[180:183], v147
	ds_read_b128 v[184:187], v147 offset:1024
	ds_read_b128 v[188:191], v147 offset:2048
	ds_read_b128 v[192:195], v147 offset:3072
	ds_read_b128 v[196:199], v147 offset:4096
	ds_read_b128 v[200:203], v147 offset:5120
	ds_read_b128 v[204:207], v147 offset:6144
	ds_read_b128 v[210:213], v147 offset:7168
	global_load_lds_dwordx4 v[214:215], off
	v_lshl_add_u64 v[214:215], s[4:5], 0, v[138:139]
	s_add_i32 m0, s48, 0xe000
	s_nop 0
	global_load_lds_dwordx4 v[214:215], off
	s_waitcnt vmcnt(8)
	s_waitcnt lgkmcnt(0)
	s_barrier
	s_setprio 1
	s_waitcnt lgkmcnt(0)
	v_mfma_f32_16x16x32_bf16 v[118:121], v[142:145], v[180:183], v[118:121]
	v_mfma_f32_16x16x32_bf16 v[122:125], v[156:159], v[180:183], v[122:125]
	v_mfma_f32_16x16x32_bf16 v[94:97], v[142:145], v[188:191], v[94:97]
	v_mfma_f32_16x16x32_bf16 v[106:109], v[156:159], v[188:191], v[106:109]
	v_mfma_f32_16x16x32_bf16 v[78:81], v[142:145], v[196:199], v[78:81]
	v_mfma_f32_16x16x32_bf16 v[90:93], v[156:159], v[196:199], v[90:93]
	v_mfma_f32_16x16x32_bf16 v[54:57], v[142:145], v[204:207], v[54:57]
	v_mfma_f32_16x16x32_bf16 v[74:77], v[156:159], v[204:207], v[74:77]
	v_mfma_f32_16x16x32_bf16 v[118:121], v[152:155], v[184:187], v[118:121]
	v_mfma_f32_16x16x32_bf16 v[122:125], v[160:163], v[184:187], v[122:125]
	v_mfma_f32_16x16x32_bf16 v[94:97], v[152:155], v[192:195], v[94:97]
	v_mfma_f32_16x16x32_bf16 v[106:109], v[160:163], v[192:195], v[106:109]
	v_mfma_f32_16x16x32_bf16 v[78:81], v[152:155], v[200:203], v[78:81]
	v_mfma_f32_16x16x32_bf16 v[90:93], v[160:163], v[200:203], v[90:93]
	v_mfma_f32_16x16x32_bf16 v[54:57], v[152:155], v[210:213], v[54:57]
	v_mfma_f32_16x16x32_bf16 v[74:77], v[160:163], v[210:213], v[74:77]
	s_setprio 0
	s_setprio 1
	v_mfma_f32_16x16x32_bf16 v[114:117], v[164:167], v[180:183], v[114:117]
	v_mfma_f32_16x16x32_bf16 v[126:129], v[172:175], v[180:183], v[126:129]
	v_mfma_f32_16x16x32_bf16 v[102:105], v[164:167], v[188:191], v[102:105]
	v_mfma_f32_16x16x32_bf16 v[110:113], v[172:175], v[188:191], v[110:113]
	v_mfma_f32_16x16x32_bf16 v[86:89], v[164:167], v[196:199], v[86:89]
	v_mfma_f32_16x16x32_bf16 v[98:101], v[172:175], v[196:199], v[98:101]
	v_mfma_f32_16x16x32_bf16 v[70:73], v[164:167], v[204:207], v[70:73]
	v_mfma_f32_16x16x32_bf16 v[82:85], v[172:175], v[204:207], v[82:85]
	v_mfma_f32_16x16x32_bf16 v[114:117], v[168:171], v[184:187], v[114:117]
	v_mfma_f32_16x16x32_bf16 v[126:129], v[176:179], v[184:187], v[126:129]
	v_mfma_f32_16x16x32_bf16 v[102:105], v[168:171], v[192:195], v[102:105]
	v_mfma_f32_16x16x32_bf16 v[110:113], v[176:179], v[192:195], v[110:113]
	v_mfma_f32_16x16x32_bf16 v[86:89], v[168:171], v[200:203], v[86:89]
	v_mfma_f32_16x16x32_bf16 v[98:101], v[176:179], v[200:203], v[98:101]
	s_setprio 3
	s_barrier
	v_mfma_f32_16x16x32_bf16 v[70:73], v[168:171], v[210:213], v[70:73]
	v_mfma_f32_16x16x32_bf16 v[82:85], v[176:179], v[210:213], v[82:85]
	s_setprio 0
	s_add_i32 s43, s67, s45
	v_lshl_add_u64 v[214:215], s[78:79], 0, v[130:131]
	s_mov_b32 m0, s43
	ds_read_b128 v[180:183], v147 offset:16384
	ds_read_b128 v[184:187], v147 offset:17408
	ds_read_b128 v[188:191], v147 offset:18432
	ds_read_b128 v[192:195], v147 offset:19456
	ds_read_b128 v[196:199], v147 offset:20480
	ds_read_b128 v[200:203], v147 offset:21504
	ds_read_b128 v[204:207], v147 offset:22528
	ds_read_b128 v[210:213], v147 offset:23552
	global_load_lds_dwordx4 v[214:215], off
	s_add_i32 m0, s43, 0x2000
	v_lshl_add_u64 v[216:217], s[78:79], 0, v[132:133]
	s_add_u32 s78, s78, s14
	s_addc_u32 s79, s79, s15
	s_add_i32 s43, s70, s45
	global_load_lds_dwordx4 v[216:217], off
	v_lshl_add_u64 v[218:219], s[78:79], 0, v[130:131]
	s_mov_b32 m0, s43
	v_lshl_add_u64 v[220:221], s[78:79], 0, v[132:133]
	global_load_lds_dwordx4 v[218:219], off
	s_add_i32 m0, s43, 0x2000
	v_lshl_add_u64 v[222:223], s[40:41], 0, v[134:135]
	global_load_lds_dwordx4 v[220:221], off
	s_mov_b32 m0, s48
	v_lshl_add_u64 v[224:225], s[40:41], 0, v[136:137]
	global_load_lds_dwordx4 v[222:223], off
	s_mov_b32 m0, s49
	s_nop 0
	global_load_lds_dwordx4 v[224:225], off
	s_waitcnt vmcnt(8)
	s_waitcnt lgkmcnt(0)
	s_barrier
	s_setprio 1
	s_waitcnt lgkmcnt(0)
	v_mfma_f32_16x16x32_bf16 v[30:33], v[142:145], v[180:183], v[30:33]
	v_mfma_f32_16x16x32_bf16 v[42:45], v[156:159], v[180:183], v[42:45]
	v_mfma_f32_16x16x32_bf16 v[14:17], v[142:145], v[188:191], v[14:17]
	v_mfma_f32_16x16x32_bf16 v[26:29], v[156:159], v[188:191], v[26:29]
	v_mfma_f32_16x16x32_bf16 v[2:5], v[142:145], v[196:199], v[2:5]
	v_mfma_f32_16x16x32_bf16 v[10:13], v[156:159], v[196:199], v[10:13]
	v_mfma_f32_16x16x32_bf16 v[50:53], v[142:145], v[204:207], v[50:53]
	v_mfma_f32_16x16x32_bf16 v[58:61], v[156:159], v[204:207], v[58:61]
	v_mfma_f32_16x16x32_bf16 v[30:33], v[152:155], v[184:187], v[30:33]
	v_mfma_f32_16x16x32_bf16 v[42:45], v[160:163], v[184:187], v[42:45]
	v_mfma_f32_16x16x32_bf16 v[14:17], v[152:155], v[192:195], v[14:17]
	v_mfma_f32_16x16x32_bf16 v[26:29], v[160:163], v[192:195], v[26:29]
	v_mfma_f32_16x16x32_bf16 v[2:5], v[152:155], v[200:203], v[2:5]
	v_mfma_f32_16x16x32_bf16 v[10:13], v[160:163], v[200:203], v[10:13]
	v_mfma_f32_16x16x32_bf16 v[50:53], v[152:155], v[210:213], v[50:53]
	v_mfma_f32_16x16x32_bf16 v[58:61], v[160:163], v[210:213], v[58:61]
	s_setprio 0
	s_setprio 1
	v_mfma_f32_16x16x32_bf16 v[38:41], v[164:167], v[180:183], v[38:41]
	v_mfma_f32_16x16x32_bf16 v[62:65], v[172:175], v[180:183], v[62:65]
	v_mfma_f32_16x16x32_bf16 v[22:25], v[164:167], v[188:191], v[22:25]
	v_mfma_f32_16x16x32_bf16 v[34:37], v[172:175], v[188:191], v[34:37]
	v_mfma_f32_16x16x32_bf16 v[6:9], v[164:167], v[196:199], v[6:9]
	v_mfma_f32_16x16x32_bf16 v[18:21], v[172:175], v[196:199], v[18:21]
	v_mfma_f32_16x16x32_bf16 v[46:49], v[164:167], v[204:207], v[46:49]
	v_mfma_f32_16x16x32_bf16 v[66:69], v[172:175], v[204:207], v[66:69]
	v_mfma_f32_16x16x32_bf16 v[38:41], v[168:171], v[184:187], v[38:41]
	v_mfma_f32_16x16x32_bf16 v[62:65], v[176:179], v[184:187], v[62:65]
	v_mfma_f32_16x16x32_bf16 v[22:25], v[168:171], v[192:195], v[22:25]
	v_mfma_f32_16x16x32_bf16 v[34:37], v[176:179], v[192:195], v[34:37]
	v_mfma_f32_16x16x32_bf16 v[6:9], v[168:171], v[200:203], v[6:9]
	v_mfma_f32_16x16x32_bf16 v[18:21], v[176:179], v[200:203], v[18:21]
	s_setprio 3
	s_barrier
	v_mfma_f32_16x16x32_bf16 v[46:49], v[168:171], v[210:213], v[46:49]
	v_mfma_f32_16x16x32_bf16 v[66:69], v[176:179], v[210:213], v[66:69]
	s_setprio 0
	s_add_i32 s43, 0, 0x18000
	v_add_u32_e32 v149, s43, v146
	s_add_i32 s77, 0, 0x1c000
	ds_read_b128 v[142:145], v149
	ds_read_b128 v[152:155], v149 offset:1024
	ds_read_b128 v[156:159], v149 offset:2048
	ds_read_b128 v[160:163], v149 offset:3072
	v_add_u32_e32 v149, s77, v146
	ds_read_b128 v[164:167], v149
	ds_read_b128 v[168:171], v149 offset:1024
	ds_read_b128 v[172:175], v149 offset:2048
	ds_read_b128 v[176:179], v149 offset:3072
	s_add_u32 s40, s40, s14
	s_addc_u32 s41, s41, s15
	s_mov_b32 m0, s50
	v_lshl_add_u64 v[226:227], s[40:41], 0, v[134:135]
	ds_read_b128 v[180:183], v147 offset:32768
	ds_read_b128 v[184:187], v147 offset:33792
	ds_read_b128 v[188:191], v147 offset:34816
	ds_read_b128 v[192:195], v147 offset:35840
	ds_read_b128 v[196:199], v147 offset:36864
	ds_read_b128 v[200:203], v147 offset:37888
	ds_read_b128 v[204:207], v147 offset:38912
	ds_read_b128 v[210:213], v147 offset:39936
	global_load_lds_dwordx4 v[226:227], off
	v_lshl_add_u64 v[226:227], s[40:41], 0, v[136:137]
	s_mov_b32 m0, s51
	s_nop 0
	global_load_lds_dwordx4 v[226:227], off
	s_waitcnt vmcnt(8)
	s_waitcnt lgkmcnt(0)
	s_barrier
	s_setprio 1
	s_waitcnt lgkmcnt(0)
	v_mfma_f32_16x16x32_bf16 v[118:121], v[142:145], v[180:183], v[118:121]
	v_mfma_f32_16x16x32_bf16 v[122:125], v[156:159], v[180:183], v[122:125]
	v_mfma_f32_16x16x32_bf16 v[94:97], v[142:145], v[188:191], v[94:97]
	v_mfma_f32_16x16x32_bf16 v[106:109], v[156:159], v[188:191], v[106:109]
	v_mfma_f32_16x16x32_bf16 v[78:81], v[142:145], v[196:199], v[78:81]
	v_mfma_f32_16x16x32_bf16 v[90:93], v[156:159], v[196:199], v[90:93]
	v_mfma_f32_16x16x32_bf16 v[54:57], v[142:145], v[204:207], v[54:57]
	v_mfma_f32_16x16x32_bf16 v[74:77], v[156:159], v[204:207], v[74:77]
	v_mfma_f32_16x16x32_bf16 v[118:121], v[152:155], v[184:187], v[118:121]
	v_mfma_f32_16x16x32_bf16 v[122:125], v[160:163], v[184:187], v[122:125]
	v_mfma_f32_16x16x32_bf16 v[94:97], v[152:155], v[192:195], v[94:97]
	v_mfma_f32_16x16x32_bf16 v[106:109], v[160:163], v[192:195], v[106:109]
	v_mfma_f32_16x16x32_bf16 v[78:81], v[152:155], v[200:203], v[78:81]
	v_mfma_f32_16x16x32_bf16 v[90:93], v[160:163], v[200:203], v[90:93]
	v_mfma_f32_16x16x32_bf16 v[54:57], v[152:155], v[210:213], v[54:57]
	v_mfma_f32_16x16x32_bf16 v[74:77], v[160:163], v[210:213], v[74:77]
	s_setprio 0
	s_setprio 1
	v_mfma_f32_16x16x32_bf16 v[114:117], v[164:167], v[180:183], v[114:117]
	v_mfma_f32_16x16x32_bf16 v[126:129], v[172:175], v[180:183], v[126:129]
	v_mfma_f32_16x16x32_bf16 v[102:105], v[164:167], v[188:191], v[102:105]
	v_mfma_f32_16x16x32_bf16 v[110:113], v[172:175], v[188:191], v[110:113]
	v_mfma_f32_16x16x32_bf16 v[86:89], v[164:167], v[196:199], v[86:89]
	v_mfma_f32_16x16x32_bf16 v[98:101], v[172:175], v[196:199], v[98:101]
	v_mfma_f32_16x16x32_bf16 v[70:73], v[164:167], v[204:207], v[70:73]
	v_mfma_f32_16x16x32_bf16 v[82:85], v[172:175], v[204:207], v[82:85]
	v_mfma_f32_16x16x32_bf16 v[114:117], v[168:171], v[184:187], v[114:117]
	v_mfma_f32_16x16x32_bf16 v[126:129], v[176:179], v[184:187], v[126:129]
	v_mfma_f32_16x16x32_bf16 v[102:105], v[168:171], v[192:195], v[102:105]
	v_mfma_f32_16x16x32_bf16 v[110:113], v[176:179], v[192:195], v[110:113]
	v_mfma_f32_16x16x32_bf16 v[86:89], v[168:171], v[200:203], v[86:89]
	v_mfma_f32_16x16x32_bf16 v[98:101], v[176:179], v[200:203], v[98:101]
	s_setprio 3
	s_barrier
	v_mfma_f32_16x16x32_bf16 v[70:73], v[168:171], v[210:213], v[70:73]
	v_mfma_f32_16x16x32_bf16 v[82:85], v[176:179], v[210:213], v[82:85]
	s_setprio 0
	s_add_i32 s40, s43, s45
	v_lshl_add_u64 v[214:215], v[214:215], 0, s[20:21]
	s_mov_b32 m0, s40
	ds_read_b128 v[180:183], v147 offset:49152
	ds_read_b128 v[184:187], v147 offset:50176
	ds_read_b128 v[188:191], v147 offset:51200
	ds_read_b128 v[192:195], v147 offset:52224
	ds_read_b128 v[196:199], v147 offset:53248
	ds_read_b128 v[200:203], v147 offset:54272
	ds_read_b128 v[204:207], v147 offset:55296
	ds_read_b128 v[210:213], v147 offset:56320
	global_load_lds_dwordx4 v[214:215], off
	v_lshl_add_u64 v[214:215], v[216:217], 0, s[20:21]
	s_add_i32 m0, s40, 0x2000
	s_add_i32 s40, s77, s45
	global_load_lds_dwordx4 v[214:215], off
	v_lshl_add_u64 v[214:215], v[218:219], 0, s[20:21]
	s_mov_b32 m0, s40
	s_nop 0
	global_load_lds_dwordx4 v[214:215], off
	v_lshl_add_u64 v[214:215], v[220:221], 0, s[20:21]
	s_add_i32 m0, s40, 0x2000
	s_nop 0
	global_load_lds_dwordx4 v[214:215], off
	v_lshl_add_u64 v[214:215], v[222:223], 0, s[20:21]
	s_mov_b32 m0, s54
	s_nop 0
	global_load_lds_dwordx4 v[214:215], off
	v_lshl_add_u64 v[214:215], v[224:225], 0, s[20:21]
	s_mov_b32 m0, s55
	s_nop 0
	global_load_lds_dwordx4 v[214:215], off
	s_waitcnt vmcnt(8)
	s_waitcnt lgkmcnt(0)
	s_barrier
	s_setprio 1
	s_waitcnt lgkmcnt(0)
	v_mfma_f32_16x16x32_bf16 v[30:33], v[142:145], v[180:183], v[30:33]
	v_mfma_f32_16x16x32_bf16 v[42:45], v[156:159], v[180:183], v[42:45]
	v_mfma_f32_16x16x32_bf16 v[14:17], v[142:145], v[188:191], v[14:17]
	v_mfma_f32_16x16x32_bf16 v[26:29], v[156:159], v[188:191], v[26:29]
	v_mfma_f32_16x16x32_bf16 v[2:5], v[142:145], v[196:199], v[2:5]
	v_mfma_f32_16x16x32_bf16 v[10:13], v[156:159], v[196:199], v[10:13]
	v_mfma_f32_16x16x32_bf16 v[50:53], v[142:145], v[204:207], v[50:53]
	v_mfma_f32_16x16x32_bf16 v[58:61], v[156:159], v[204:207], v[58:61]
	v_mfma_f32_16x16x32_bf16 v[30:33], v[152:155], v[184:187], v[30:33]
	v_mfma_f32_16x16x32_bf16 v[42:45], v[160:163], v[184:187], v[42:45]
	v_mfma_f32_16x16x32_bf16 v[14:17], v[152:155], v[192:195], v[14:17]
	v_mfma_f32_16x16x32_bf16 v[26:29], v[160:163], v[192:195], v[26:29]
	v_mfma_f32_16x16x32_bf16 v[2:5], v[152:155], v[200:203], v[2:5]
	v_mfma_f32_16x16x32_bf16 v[10:13], v[160:163], v[200:203], v[10:13]
	v_mfma_f32_16x16x32_bf16 v[50:53], v[152:155], v[210:213], v[50:53]
	v_mfma_f32_16x16x32_bf16 v[58:61], v[160:163], v[210:213], v[58:61]
	s_setprio 0
	s_setprio 1
	v_mfma_f32_16x16x32_bf16 v[38:41], v[164:167], v[180:183], v[38:41]
	v_mfma_f32_16x16x32_bf16 v[62:65], v[172:175], v[180:183], v[62:65]
	v_mfma_f32_16x16x32_bf16 v[22:25], v[164:167], v[188:191], v[22:25]
	v_mfma_f32_16x16x32_bf16 v[34:37], v[172:175], v[188:191], v[34:37]
	v_mfma_f32_16x16x32_bf16 v[6:9], v[164:167], v[196:199], v[6:9]
	v_mfma_f32_16x16x32_bf16 v[18:21], v[172:175], v[196:199], v[18:21]
	v_mfma_f32_16x16x32_bf16 v[46:49], v[164:167], v[204:207], v[46:49]
	v_mfma_f32_16x16x32_bf16 v[66:69], v[172:175], v[204:207], v[66:69]
	v_mfma_f32_16x16x32_bf16 v[38:41], v[168:171], v[184:187], v[38:41]
	v_mfma_f32_16x16x32_bf16 v[62:65], v[176:179], v[184:187], v[62:65]
	v_mfma_f32_16x16x32_bf16 v[22:25], v[168:171], v[192:195], v[22:25]
	v_mfma_f32_16x16x32_bf16 v[34:37], v[176:179], v[192:195], v[34:37]
	v_mfma_f32_16x16x32_bf16 v[6:9], v[168:171], v[200:203], v[6:9]
	v_mfma_f32_16x16x32_bf16 v[18:21], v[176:179], v[200:203], v[18:21]
	s_setprio 3
	s_barrier
	v_mfma_f32_16x16x32_bf16 v[46:49], v[168:171], v[210:213], v[46:49]
	v_mfma_f32_16x16x32_bf16 v[66:69], v[176:179], v[210:213], v[66:69]
	s_setprio 0
	s_add_u32 s75, s75, 0x100
	s_addc_u32 s76, s76, 0
	s_add_u32 s4, s4, 0x100
	s_addc_u32 s5, s5, 0
	s_cmp_ge_i32 s42, s53
	s_mov_b32 s40, s42
	s_cbranch_scc0 .LBB0_1297

.LBB0_1446:
	s_add_i32 s36, s44, 2
	ds_read_b128 v[140:143], v192
	ds_read_b128 v[144:147], v192 offset:1024
	ds_read_b128 v[148:151], v192 offset:2048
	ds_read_b128 v[152:155], v192 offset:3072
	ds_read_b128 v[156:159], v193
	ds_read_b128 v[160:163], v193 offset:1024
	ds_read_b128 v[164:167], v193 offset:2048
	ds_read_b128 v[168:171], v193 offset:3072
	s_or_b32 s72, s44, 1
	s_lshl_b64 s[74:75], s[36:37], 7
	s_add_u32 s71, s0, s74
	s_addc_u32 s45, s1, s75
	s_cmp_eq_u32 s44, s55
	s_cselect_b32 s74, 0, s74
	s_mov_b32 s73, s37
	s_cselect_b32 s45, s43, s45
	s_cselect_b32 s44, s42, s71
	s_cselect_b32 s71, 0, s75
	s_add_u32 s74, s22, s74
	s_addc_u32 s75, s23, s71
	s_lshl_b64 s[72:73], s[72:73], 7
	s_add_u32 s72, s69, s72
	s_addc_u32 s73, s70, s73
	s_mov_b32 m0, s56
	v_lshl_add_u64 v[188:189], s[72:73], 0, v[134:135]
	ds_read_b128 v[172:175], v194
	ds_read_b128 v[176:179], v194 offset:1024
	ds_read_b128 v[180:183], v194 offset:2048
	ds_read_b128 v[184:187], v194 offset:3072
	ds_read_b128 v[200:203], v194 offset:4096
	ds_read_b128 v[204:207], v194 offset:5120
	ds_read_b128 v[210:213], v194 offset:6144
	ds_read_b128 v[214:217], v194 offset:7168
	global_load_lds_dwordx4 v[188:189], off
	v_lshl_add_u64 v[188:189], s[72:73], 0, v[136:137]
	s_mov_b32 m0, s57
	s_nop 0
	global_load_lds_dwordx4 v[188:189], off
	s_waitcnt vmcnt(8)
	s_waitcnt lgkmcnt(0)
	s_barrier
	s_setprio 1
	s_waitcnt lgkmcnt(0)
	v_mfma_f32_16x16x32_bf16 v[126:129], v[140:143], v[172:175], v[126:129]
	v_mfma_f32_16x16x32_bf16 v[122:125], v[148:151], v[172:175], v[122:125]
	v_mfma_f32_16x16x32_bf16 v[110:113], v[140:143], v[180:183], v[110:113]
	v_mfma_f32_16x16x32_bf16 v[106:109], v[148:151], v[180:183], v[106:109]
	v_mfma_f32_16x16x32_bf16 v[94:97], v[140:143], v[200:203], v[94:97]
	v_mfma_f32_16x16x32_bf16 v[90:93], v[148:151], v[200:203], v[90:93]
	v_mfma_f32_16x16x32_bf16 v[78:81], v[140:143], v[210:213], v[78:81]
	v_mfma_f32_16x16x32_bf16 v[74:77], v[148:151], v[210:213], v[74:77]
	v_mfma_f32_16x16x32_bf16 v[126:129], v[144:147], v[176:179], v[126:129]
	v_mfma_f32_16x16x32_bf16 v[122:125], v[152:155], v[176:179], v[122:125]
	v_mfma_f32_16x16x32_bf16 v[110:113], v[144:147], v[184:187], v[110:113]
	v_mfma_f32_16x16x32_bf16 v[106:109], v[152:155], v[184:187], v[106:109]
	v_mfma_f32_16x16x32_bf16 v[94:97], v[144:147], v[204:207], v[94:97]
	v_mfma_f32_16x16x32_bf16 v[90:93], v[152:155], v[204:207], v[90:93]
	v_mfma_f32_16x16x32_bf16 v[78:81], v[144:147], v[214:217], v[78:81]
	v_mfma_f32_16x16x32_bf16 v[74:77], v[152:155], v[214:217], v[74:77]
	s_setprio 0
	s_setprio 1
	v_mfma_f32_16x16x32_bf16 v[118:121], v[156:159], v[172:175], v[118:121]
	v_mfma_f32_16x16x32_bf16 v[114:117], v[164:167], v[172:175], v[114:117]
	v_mfma_f32_16x16x32_bf16 v[102:105], v[156:159], v[180:183], v[102:105]
	v_mfma_f32_16x16x32_bf16 v[98:101], v[164:167], v[180:183], v[98:101]
	v_mfma_f32_16x16x32_bf16 v[86:89], v[156:159], v[200:203], v[86:89]
	v_mfma_f32_16x16x32_bf16 v[82:85], v[164:167], v[200:203], v[82:85]
	v_mfma_f32_16x16x32_bf16 v[70:73], v[156:159], v[210:213], v[70:73]
	v_mfma_f32_16x16x32_bf16 v[66:69], v[164:167], v[210:213], v[66:69]
	v_mfma_f32_16x16x32_bf16 v[118:121], v[160:163], v[176:179], v[118:121]
	v_mfma_f32_16x16x32_bf16 v[114:117], v[168:171], v[176:179], v[114:117]
	v_mfma_f32_16x16x32_bf16 v[102:105], v[160:163], v[184:187], v[102:105]
	v_mfma_f32_16x16x32_bf16 v[98:101], v[168:171], v[184:187], v[98:101]
	v_mfma_f32_16x16x32_bf16 v[86:89], v[160:163], v[204:207], v[86:89]
	v_mfma_f32_16x16x32_bf16 v[82:85], v[168:171], v[204:207], v[82:85]
	s_setprio 3
	s_barrier
	v_mfma_f32_16x16x32_bf16 v[70:73], v[160:163], v[214:217], v[70:73]
	v_mfma_f32_16x16x32_bf16 v[66:69], v[168:171], v[214:217], v[66:69]
	s_setprio 0
	s_mov_b32 m0, s58
	v_lshl_add_u64 v[188:189], s[74:75], 0, v[130:131]
	s_add_u32 s72, s74, s24
	ds_read_b128 v[172:175], v194 offset:16384
	ds_read_b128 v[176:179], v194 offset:17408
	ds_read_b128 v[180:183], v194 offset:18432
	ds_read_b128 v[184:187], v194 offset:19456
	ds_read_b128 v[200:203], v194 offset:20480
	ds_read_b128 v[204:207], v194 offset:21504
	ds_read_b128 v[210:213], v194 offset:22528
	ds_read_b128 v[214:217], v194 offset:23552
	global_load_lds_dwordx4 v[188:189], off
	v_lshl_add_u64 v[218:219], s[74:75], 0, v[132:133]
	s_mov_b32 m0, s59
	s_addc_u32 s73, s75, s25
	global_load_lds_dwordx4 v[218:219], off
	v_lshl_add_u64 v[220:221], s[72:73], 0, v[130:131]
	s_mov_b32 m0, s60
	v_lshl_add_u64 v[222:223], s[72:73], 0, v[132:133]
	global_load_lds_dwordx4 v[220:221], off
	s_mov_b32 m0, s61
	v_lshl_add_u64 v[224:225], s[44:45], 0, v[134:135]
	global_load_lds_dwordx4 v[222:223], off
	s_mov_b32 m0, s33
	v_lshl_add_u64 v[226:227], s[44:45], 0, v[136:137]
	global_load_lds_dwordx4 v[224:225], off
	s_mov_b32 m0, s35
	s_nop 0
	global_load_lds_dwordx4 v[226:227], off
	s_waitcnt vmcnt(8)
	s_waitcnt lgkmcnt(0)
	s_barrier
	s_setprio 1
	s_waitcnt lgkmcnt(0)
	v_mfma_f32_16x16x32_bf16 v[62:65], v[140:143], v[172:175], v[62:65]
	v_mfma_f32_16x16x32_bf16 v[58:61], v[148:151], v[172:175], v[58:61]
	v_mfma_f32_16x16x32_bf16 v[46:49], v[140:143], v[180:183], v[46:49]
	v_mfma_f32_16x16x32_bf16 v[42:45], v[148:151], v[180:183], v[42:45]
	v_mfma_f32_16x16x32_bf16 v[30:33], v[140:143], v[200:203], v[30:33]
	v_mfma_f32_16x16x32_bf16 v[26:29], v[148:151], v[200:203], v[26:29]
	v_mfma_f32_16x16x32_bf16 v[14:17], v[140:143], v[210:213], v[14:17]
	v_mfma_f32_16x16x32_bf16 v[10:13], v[148:151], v[210:213], v[10:13]
	v_mfma_f32_16x16x32_bf16 v[62:65], v[144:147], v[176:179], v[62:65]
	v_mfma_f32_16x16x32_bf16 v[58:61], v[152:155], v[176:179], v[58:61]
	v_mfma_f32_16x16x32_bf16 v[46:49], v[144:147], v[184:187], v[46:49]
	v_mfma_f32_16x16x32_bf16 v[42:45], v[152:155], v[184:187], v[42:45]
	v_mfma_f32_16x16x32_bf16 v[30:33], v[144:147], v[204:207], v[30:33]
	v_mfma_f32_16x16x32_bf16 v[26:29], v[152:155], v[204:207], v[26:29]
	v_mfma_f32_16x16x32_bf16 v[14:17], v[144:147], v[214:217], v[14:17]
	v_mfma_f32_16x16x32_bf16 v[10:13], v[152:155], v[214:217], v[10:13]
	s_setprio 0
	s_setprio 1
	v_mfma_f32_16x16x32_bf16 v[54:57], v[156:159], v[172:175], v[54:57]
	v_mfma_f32_16x16x32_bf16 v[50:53], v[164:167], v[172:175], v[50:53]
	v_mfma_f32_16x16x32_bf16 v[38:41], v[156:159], v[180:183], v[38:41]
	v_mfma_f32_16x16x32_bf16 v[34:37], v[164:167], v[180:183], v[34:37]
	v_mfma_f32_16x16x32_bf16 v[22:25], v[156:159], v[200:203], v[22:25]
	v_mfma_f32_16x16x32_bf16 v[18:21], v[164:167], v[200:203], v[18:21]
	v_mfma_f32_16x16x32_bf16 v[6:9], v[156:159], v[210:213], v[6:9]
	v_mfma_f32_16x16x32_bf16 v[2:5], v[164:167], v[210:213], v[2:5]
	v_mfma_f32_16x16x32_bf16 v[54:57], v[160:163], v[176:179], v[54:57]
	v_mfma_f32_16x16x32_bf16 v[50:53], v[168:171], v[176:179], v[50:53]
	v_mfma_f32_16x16x32_bf16 v[38:41], v[160:163], v[184:187], v[38:41]
	v_mfma_f32_16x16x32_bf16 v[34:37], v[168:171], v[184:187], v[34:37]
	v_mfma_f32_16x16x32_bf16 v[22:25], v[160:163], v[204:207], v[22:25]
	v_mfma_f32_16x16x32_bf16 v[18:21], v[168:171], v[204:207], v[18:21]
	s_setprio 3
	s_barrier
	v_mfma_f32_16x16x32_bf16 v[6:9], v[160:163], v[214:217], v[6:9]
	v_mfma_f32_16x16x32_bf16 v[2:5], v[168:171], v[214:217], v[2:5]
	s_setprio 0
	ds_read_b128 v[140:143], v195
	ds_read_b128 v[144:147], v195 offset:1024
	ds_read_b128 v[148:151], v195 offset:2048
	ds_read_b128 v[152:155], v195 offset:3072
	ds_read_b128 v[156:159], v196
	ds_read_b128 v[160:163], v196 offset:1024
	ds_read_b128 v[164:167], v196 offset:2048
	ds_read_b128 v[168:171], v196 offset:3072
	s_add_u32 s44, s44, s24
	s_addc_u32 s45, s45, s25
	s_mov_b32 m0, s46
	v_lshl_add_u64 v[228:229], s[44:45], 0, v[134:135]
	ds_read_b128 v[172:175], v194 offset:32768
	ds_read_b128 v[176:179], v194 offset:33792
	ds_read_b128 v[180:183], v194 offset:34816
	ds_read_b128 v[184:187], v194 offset:35840
	ds_read_b128 v[200:203], v194 offset:36864
	ds_read_b128 v[204:207], v194 offset:37888
	ds_read_b128 v[210:213], v194 offset:38912
	ds_read_b128 v[214:217], v194 offset:39936
	global_load_lds_dwordx4 v[228:229], off
	v_lshl_add_u64 v[228:229], s[44:45], 0, v[136:137]
	s_mov_b32 m0, s47
	s_nop 0
	global_load_lds_dwordx4 v[228:229], off
	s_waitcnt vmcnt(8)
	s_waitcnt lgkmcnt(0)
	s_barrier
	s_setprio 1
	s_waitcnt lgkmcnt(0)
	v_mfma_f32_16x16x32_bf16 v[126:129], v[140:143], v[172:175], v[126:129]
	v_mfma_f32_16x16x32_bf16 v[122:125], v[148:151], v[172:175], v[122:125]
	v_mfma_f32_16x16x32_bf16 v[110:113], v[140:143], v[180:183], v[110:113]
	v_mfma_f32_16x16x32_bf16 v[106:109], v[148:151], v[180:183], v[106:109]
	v_mfma_f32_16x16x32_bf16 v[94:97], v[140:143], v[200:203], v[94:97]
	v_mfma_f32_16x16x32_bf16 v[90:93], v[148:151], v[200:203], v[90:93]
	v_mfma_f32_16x16x32_bf16 v[78:81], v[140:143], v[210:213], v[78:81]
	v_mfma_f32_16x16x32_bf16 v[74:77], v[148:151], v[210:213], v[74:77]
	v_mfma_f32_16x16x32_bf16 v[126:129], v[144:147], v[176:179], v[126:129]
	v_mfma_f32_16x16x32_bf16 v[122:125], v[152:155], v[176:179], v[122:125]
	v_mfma_f32_16x16x32_bf16 v[110:113], v[144:147], v[184:187], v[110:113]
	v_mfma_f32_16x16x32_bf16 v[106:109], v[152:155], v[184:187], v[106:109]
	v_mfma_f32_16x16x32_bf16 v[94:97], v[144:147], v[204:207], v[94:97]
	v_mfma_f32_16x16x32_bf16 v[90:93], v[152:155], v[204:207], v[90:93]
	v_mfma_f32_16x16x32_bf16 v[78:81], v[144:147], v[214:217], v[78:81]
	v_mfma_f32_16x16x32_bf16 v[74:77], v[152:155], v[214:217], v[74:77]
	s_setprio 0
	s_setprio 1
	v_mfma_f32_16x16x32_bf16 v[118:121], v[156:159], v[172:175], v[118:121]
	v_mfma_f32_16x16x32_bf16 v[114:117], v[164:167], v[172:175], v[114:117]
	v_mfma_f32_16x16x32_bf16 v[102:105], v[156:159], v[180:183], v[102:105]
	v_mfma_f32_16x16x32_bf16 v[98:101], v[164:167], v[180:183], v[98:101]
	v_mfma_f32_16x16x32_bf16 v[86:89], v[156:159], v[200:203], v[86:89]
	v_mfma_f32_16x16x32_bf16 v[82:85], v[164:167], v[200:203], v[82:85]
	v_mfma_f32_16x16x32_bf16 v[70:73], v[156:159], v[210:213], v[70:73]
	v_mfma_f32_16x16x32_bf16 v[66:69], v[164:167], v[210:213], v[66:69]
	v_mfma_f32_16x16x32_bf16 v[118:121], v[160:163], v[176:179], v[118:121]
	v_mfma_f32_16x16x32_bf16 v[114:117], v[168:171], v[176:179], v[114:117]
	v_mfma_f32_16x16x32_bf16 v[102:105], v[160:163], v[184:187], v[102:105]
	v_mfma_f32_16x16x32_bf16 v[98:101], v[168:171], v[184:187], v[98:101]
	v_mfma_f32_16x16x32_bf16 v[86:89], v[160:163], v[204:207], v[86:89]
	v_mfma_f32_16x16x32_bf16 v[82:85], v[168:171], v[204:207], v[82:85]
	s_setprio 3
	s_barrier
	v_mfma_f32_16x16x32_bf16 v[70:73], v[160:163], v[214:217], v[70:73]
	v_mfma_f32_16x16x32_bf16 v[66:69], v[168:171], v[214:217], v[66:69]
	s_setprio 0
	s_mov_b32 m0, s62
	v_lshl_add_u64 v[188:189], v[188:189], 0, s[18:19]
	ds_read_b128 v[172:175], v194 offset:49152
	ds_read_b128 v[176:179], v194 offset:50176
	ds_read_b128 v[180:183], v194 offset:51200
	ds_read_b128 v[184:187], v194 offset:52224
	ds_read_b128 v[200:203], v194 offset:53248
	ds_read_b128 v[204:207], v194 offset:54272
	ds_read_b128 v[210:213], v194 offset:55296
	ds_read_b128 v[214:217], v194 offset:56320
	global_load_lds_dwordx4 v[188:189], off
	v_lshl_add_u64 v[188:189], v[218:219], 0, s[18:19]
	s_mov_b32 m0, s63
	s_nop 0
	global_load_lds_dwordx4 v[188:189], off
	v_lshl_add_u64 v[188:189], v[220:221], 0, s[18:19]
	s_mov_b32 m0, s64
	s_nop 0
	global_load_lds_dwordx4 v[188:189], off
	v_lshl_add_u64 v[188:189], v[222:223], 0, s[18:19]
	s_mov_b32 m0, s65
	s_nop 0
	global_load_lds_dwordx4 v[188:189], off
	v_lshl_add_u64 v[188:189], v[224:225], 0, s[18:19]
	s_mov_b32 m0, s50
	s_nop 0
	global_load_lds_dwordx4 v[188:189], off
	v_lshl_add_u64 v[188:189], v[226:227], 0, s[18:19]
	s_mov_b32 m0, s51
	s_nop 0
	global_load_lds_dwordx4 v[188:189], off
	s_waitcnt vmcnt(8)
	s_waitcnt lgkmcnt(0)
	s_barrier
	s_setprio 1
	s_waitcnt lgkmcnt(0)
	v_mfma_f32_16x16x32_bf16 v[62:65], v[140:143], v[172:175], v[62:65]
	v_mfma_f32_16x16x32_bf16 v[58:61], v[148:151], v[172:175], v[58:61]
	v_mfma_f32_16x16x32_bf16 v[46:49], v[140:143], v[180:183], v[46:49]
	v_mfma_f32_16x16x32_bf16 v[42:45], v[148:151], v[180:183], v[42:45]
	v_mfma_f32_16x16x32_bf16 v[30:33], v[140:143], v[200:203], v[30:33]
	v_mfma_f32_16x16x32_bf16 v[26:29], v[148:151], v[200:203], v[26:29]
	v_mfma_f32_16x16x32_bf16 v[14:17], v[140:143], v[210:213], v[14:17]
	v_mfma_f32_16x16x32_bf16 v[10:13], v[148:151], v[210:213], v[10:13]
	v_mfma_f32_16x16x32_bf16 v[62:65], v[144:147], v[176:179], v[62:65]
	v_mfma_f32_16x16x32_bf16 v[58:61], v[152:155], v[176:179], v[58:61]
	v_mfma_f32_16x16x32_bf16 v[46:49], v[144:147], v[184:187], v[46:49]
	v_mfma_f32_16x16x32_bf16 v[42:45], v[152:155], v[184:187], v[42:45]
	v_mfma_f32_16x16x32_bf16 v[30:33], v[144:147], v[204:207], v[30:33]
	v_mfma_f32_16x16x32_bf16 v[26:29], v[152:155], v[204:207], v[26:29]
	v_mfma_f32_16x16x32_bf16 v[14:17], v[144:147], v[214:217], v[14:17]
	v_mfma_f32_16x16x32_bf16 v[10:13], v[152:155], v[214:217], v[10:13]
	s_setprio 0
	s_setprio 1
	v_mfma_f32_16x16x32_bf16 v[54:57], v[156:159], v[172:175], v[54:57]
	v_mfma_f32_16x16x32_bf16 v[50:53], v[164:167], v[172:175], v[50:53]
	v_mfma_f32_16x16x32_bf16 v[38:41], v[156:159], v[180:183], v[38:41]
	v_mfma_f32_16x16x32_bf16 v[34:37], v[164:167], v[180:183], v[34:37]
	v_mfma_f32_16x16x32_bf16 v[22:25], v[156:159], v[200:203], v[22:25]
	v_mfma_f32_16x16x32_bf16 v[18:21], v[164:167], v[200:203], v[18:21]
	v_mfma_f32_16x16x32_bf16 v[6:9], v[156:159], v[210:213], v[6:9]
	v_mfma_f32_16x16x32_bf16 v[2:5], v[164:167], v[210:213], v[2:5]
	v_mfma_f32_16x16x32_bf16 v[54:57], v[160:163], v[176:179], v[54:57]
	v_mfma_f32_16x16x32_bf16 v[50:53], v[168:171], v[176:179], v[50:53]
	v_mfma_f32_16x16x32_bf16 v[38:41], v[160:163], v[184:187], v[38:41]
	v_mfma_f32_16x16x32_bf16 v[34:37], v[168:171], v[184:187], v[34:37]
	v_mfma_f32_16x16x32_bf16 v[22:25], v[160:163], v[204:207], v[22:25]
	v_mfma_f32_16x16x32_bf16 v[18:21], v[168:171], v[204:207], v[18:21]
	s_setprio 3
	s_barrier
	v_mfma_f32_16x16x32_bf16 v[6:9], v[160:163], v[214:217], v[6:9]
	v_mfma_f32_16x16x32_bf16 v[2:5], v[168:171], v[214:217], v[2:5]
	s_setprio 0
	s_cmp_ge_i32 s36, s54
	s_mov_b32 s44, s36
	s_cbranch_scc0 .LBB0_1446
	v_readlane_b32 s72, v235, 8
	v_readlane_b32 s74, v235, 10
	v_readlane_b32 s75, v235, 11
	v_readlane_b32 s86, v235, 22
	v_readlane_b32 s87, v235, 23
	s_mov_b64 s[74:75], s[86:87]
	v_readlane_b32 s73, v235, 9
	v_readlane_b32 s76, v235, 12
	v_readlane_b32 s77, v235, 13
	v_readlane_b32 s78, v235, 14
	v_readlane_b32 s79, v235, 15
	v_readlane_b32 s80, v235, 16
	v_readlane_b32 s81, v235, 17
	v_readlane_b32 s82, v235, 18
	v_readlane_b32 s83, v235, 19
	v_readlane_b32 s84, v235, 20
	v_readlane_b32 s85, v235, 21
